# GEMM1/GEMM2 epilogues: sigmoid/silu 1/x via single v_rcp_f32 instead of the IEEE division expansion (f32, results rounded to bf16)
# speedup vs baseline: 1.0237x; 1.0020x over previous
.LBB0_477:
	s_and_b64 vcc, exec, s[6:7]
	s_cbranch_vccz .LBB0_479
	v_lshl_add_u64 v[156:157], v[136:137], 2, s[22:23]
	global_load_dword v172, v[156:157], off
	v_mov_b64_e32 v[158:159], s[34:35]
	v_lshl_add_u64 v[160:161], v[134:135], 2, s[22:23]
	v_lshl_add_u64 v[162:163], v[132:133], 2, s[22:23]
	v_lshl_add_u64 v[164:165], v[130:131], 2, s[22:23]
	v_add_u32_e32 v137, 0x80, v136
	v_add_u32_e32 v135, 0x90, v136
	v_add_u32_e32 v133, 0xa0, v136
	v_add_u32_e32 v131, 0xb0, v136
	v_mad_i64_i32 v[174:175], s[0:1], v136, s92, v[158:159]
	global_load_dword v170, v[160:161], off
	global_load_dword v168, v[162:163], off
	global_load_dword v166, v[164:165], off
	s_nop 0
	global_load_dword v164, v[156:157], off offset:512
	global_load_dword v162, v[156:157], off offset:576
	global_load_dword v160, v[156:157], off offset:640
	s_nop 0
	global_load_dword v156, v[156:157], off offset:704
	s_waitcnt vmcnt(0)
	v_pk_mul_f32 v[180:181], v[126:127], v[172:173] op_sel_hi:[1,0]
	v_pk_mul_f32 v[184:185], v[122:123], v[172:173] op_sel_hi:[1,0]
	v_mul_f32_e32 v136, 0xbfb8aa3b, v180
	v_mul_f32_e32 v148, 0xbfb8aa3b, v184
	v_exp_f32_e32 v136, v136
	v_mul_f32_e32 v157, 0xbfb8aa3b, v181
	v_exp_f32_e32 v148, v148
	v_mul_f32_e32 v161, 0xbfb8aa3b, v185
	v_exp_f32_e32 v157, v157
	v_exp_f32_e32 v161, v161
	v_add_f32_e32 v136, 1.0, v136
	v_pk_mul_f32 v[176:177], v[128:129], v[172:173] op_sel_hi:[1,0]
	v_add_f32_e32 v148, 1.0, v148
	v_mul_f32_e32 v163, 0xbfb8aa3b, v176
	v_add_f32_e32 v157, 1.0, v157
	v_exp_f32_e32 v163, v163
	v_add_f32_e32 v161, 1.0, v161
	v_add_f32_e32 v163, 1.0, v163
	v_pk_mul_f32 v[182:183], v[124:125], v[172:173] op_sel_hi:[1,0]
	v_mul_f32_e32 v165, 0xbfb8aa3b, v182
	v_exp_f32_e32 v165, v165
	v_rcp_f32_e32 v136, v136
	v_rcp_f32_e32 v167, v148
	v_add_f32_e32 v165, 1.0, v165
	v_rcp_f32_e32 v157, v157
	v_rcp_f32_e32 v161, v161
	v_rcp_f32_e32 v163, v163
	v_mul_f32_e32 v176, 0xbfb8aa3b, v177
	v_exp_f32_e32 v176, v176
	s_nop 0
	v_add_f32_e32 v169, 1.0, v176
	v_mul_f32_e32 v173, 0xbfb8aa3b, v183
	v_rcp_f32_e32 v165, v165
	v_exp_f32_e32 v173, v173
	s_nop 0
	v_add_f32_e32 v173, 1.0, v173
	v_rcp_f32_e32 v169, v169
	v_pk_mul_f32 v[182:183], v[118:119], v[172:173] op_sel_hi:[1,0]
	v_rcp_f32_e32 v171, v173
	v_lshlrev_b32_e32 v148, 1, v189
	v_lshl_or_b32 v148, s68, 9, v148
	v_lshl_add_u64 v[180:181], v[174:175], 0, v[148:149]
	v_cvt_pk_bf16_f32 v174, v136, v157
	v_mul_f32_e32 v136, 0xbfb8aa3b, v182
	v_exp_f32_e32 v136, v136
	v_cvt_pk_bf16_f32 v176, v167, v161
	v_cvt_pk_bf16_f32 v175, v163, v169
	v_cvt_pk_bf16_f32 v177, v165, v171
	global_store_dwordx4 v[180:181], v[174:177], off
	s_nop 0
	v_add_f32_e32 v136, 1.0, v136
	v_pk_mul_f32 v[174:175], v[120:121], v[172:173] op_sel_hi:[1,0]
	v_pk_mul_f32 v[176:177], v[116:117], v[172:173] op_sel_hi:[1,0]
	v_pk_mul_f32 v[172:173], v[114:115], v[172:173] op_sel_hi:[1,0]
	v_mul_f32_e32 v167, 0xbfb8aa3b, v172
	v_exp_f32_e32 v167, v167
	s_nop 0
	v_add_f32_e32 v163, 1.0, v167
	v_mul_f32_e32 v165, 0xbfb8aa3b, v183
	v_rcp_f32_e32 v136, v136
	v_exp_f32_e32 v165, v165
	s_nop 0
	v_add_f32_e32 v165, 1.0, v165
	v_mul_f32_e32 v169, 0xbfb8aa3b, v173
	v_exp_f32_e32 v169, v169
	v_rcp_f32_e32 v157, v163
	v_add_f32_e32 v167, 1.0, v169
	v_mul_f32_e32 v171, 0xbfb8aa3b, v174
	v_exp_f32_e32 v171, v171
	v_rcp_f32_e32 v161, v165
	v_add_f32_e32 v169, 1.0, v171
	v_mul_f32_e32 v172, 0xbfb8aa3b, v176
	v_exp_f32_e32 v172, v172
	v_rcp_f32_e32 v163, v167
	v_add_f32_e32 v171, 1.0, v172
	v_mul_f32_e32 v173, 0xbfb8aa3b, v175
	v_exp_f32_e32 v173, v173
	v_rcp_f32_e32 v165, v169
	v_add_f32_e32 v172, 1.0, v173
	v_mul_f32_e32 v174, 0xbfb8aa3b, v177
	v_exp_f32_e32 v174, v174
	v_rcp_f32_e32 v167, v171
	v_add_f32_e32 v173, 1.0, v174
	v_rcp_f32_e32 v169, v172
	v_rcp_f32_e32 v171, v173
	s_nop 0
	v_pk_mul_f32 v[176:177], v[110:111], v[170:171] op_sel_hi:[1,0]
	v_cvt_pk_bf16_f32 v172, v136, v161
	v_cvt_pk_bf16_f32 v173, v165, v169
	v_cvt_pk_bf16_f32 v174, v157, v163
	v_cvt_pk_bf16_f32 v175, v167, v171
	global_store_dwordx4 v[180:181], v[172:175], off offset:256
	v_mul_f32_e32 v136, 0xbfb8aa3b, v176
	v_exp_f32_e32 v136, v136
	v_mad_i64_i32 v[172:173], s[0:1], v134, s92, v[158:159]
	v_pk_mul_f32 v[182:183], v[106:107], v[170:171] op_sel_hi:[1,0]
	v_add_f32_e32 v134, 1.0, v136
	v_mul_f32_e32 v165, 0xbfb8aa3b, v182
	v_exp_f32_e32 v165, v165
	v_pk_mul_f32 v[174:175], v[112:113], v[170:171] op_sel_hi:[1,0]
	v_add_f32_e32 v161, 1.0, v165
	v_mul_f32_e32 v163, 0xbfb8aa3b, v177
	v_rcp_f32_e32 v134, v134
	v_exp_f32_e32 v163, v163
	s_nop 0
	v_add_f32_e32 v163, 1.0, v163
	v_mul_f32_e32 v167, 0xbfb8aa3b, v183
	v_exp_f32_e32 v167, v167
	v_rcp_f32_e32 v136, v161
	v_pk_mul_f32 v[180:181], v[108:109], v[170:171] op_sel_hi:[1,0]
	v_add_f32_e32 v165, 1.0, v167
	v_mul_f32_e32 v169, 0xbfb8aa3b, v174
	v_exp_f32_e32 v169, v169
	v_rcp_f32_e32 v157, v163
	v_add_f32_e32 v167, 1.0, v169
	v_mul_f32_e32 v171, 0xbfb8aa3b, v180
	v_exp_f32_e32 v171, v171
	v_rcp_f32_e32 v161, v165
	v_add_f32_e32 v169, 1.0, v171
	v_mul_f32_e32 v174, 0xbfb8aa3b, v175
	v_exp_f32_e32 v174, v174
	v_rcp_f32_e32 v163, v167
	v_add_f32_e32 v171, 1.0, v174
	v_mul_f32_e32 v176, 0xbfb8aa3b, v181
	v_exp_f32_e32 v176, v176
	v_rcp_f32_e32 v165, v169
	v_add_f32_e32 v174, 1.0, v176
	v_rcp_f32_e32 v167, v171
	v_pk_mul_f32 v[180:181], v[102:103], v[170:171] op_sel_hi:[1,0]
	v_lshl_add_u64 v[176:177], v[172:173], 0, v[148:149]
	v_cvt_pk_bf16_f32 v172, v134, v157
	v_mul_f32_e32 v134, 0xbfb8aa3b, v180
	v_exp_f32_e32 v134, v134
	v_rcp_f32_e32 v169, v174
	v_cvt_pk_bf16_f32 v174, v136, v161
	v_cvt_pk_bf16_f32 v173, v163, v167
	v_add_f32_e32 v134, 1.0, v134
	v_cvt_pk_bf16_f32 v175, v165, v169
	global_store_dwordx4 v[176:177], v[172:175], off
	s_nop 0
	s_nop 0
	v_pk_mul_f32 v[172:173], v[104:105], v[170:171] op_sel_hi:[1,0]
	v_pk_mul_f32 v[174:175], v[100:101], v[170:171] op_sel_hi:[1,0]
	v_pk_mul_f32 v[170:171], v[98:99], v[170:171] op_sel_hi:[1,0]
	v_mul_f32_e32 v165, 0xbfb8aa3b, v170
	v_exp_f32_e32 v165, v165
	s_nop 0
	v_add_f32_e32 v161, 1.0, v165
	v_mul_f32_e32 v163, 0xbfb8aa3b, v181
	v_rcp_f32_e32 v134, v134
	v_exp_f32_e32 v163, v163
	s_nop 0
	v_add_f32_e32 v163, 1.0, v163
	v_mul_f32_e32 v167, 0xbfb8aa3b, v171
	v_exp_f32_e32 v167, v167
	v_rcp_f32_e32 v136, v161
	v_add_f32_e32 v165, 1.0, v167
	v_mul_f32_e32 v169, 0xbfb8aa3b, v172
	v_exp_f32_e32 v169, v169
	v_rcp_f32_e32 v157, v163
	v_add_f32_e32 v167, 1.0, v169
	v_mul_f32_e32 v170, 0xbfb8aa3b, v174
	v_exp_f32_e32 v170, v170
	v_rcp_f32_e32 v161, v165
	v_add_f32_e32 v169, 1.0, v170
	v_mul_f32_e32 v171, 0xbfb8aa3b, v173
	v_exp_f32_e32 v171, v171
	v_rcp_f32_e32 v163, v167
	v_add_f32_e32 v170, 1.0, v171
	v_mul_f32_e32 v172, 0xbfb8aa3b, v175
	v_exp_f32_e32 v172, v172
	v_rcp_f32_e32 v165, v169
	v_add_f32_e32 v171, 1.0, v172
	v_rcp_f32_e32 v167, v170
	v_rcp_f32_e32 v169, v171
	s_nop 0
	v_pk_mul_f32 v[174:175], v[94:95], v[168:169] op_sel_hi:[1,0]
	v_cvt_pk_bf16_f32 v170, v134, v157
	v_cvt_pk_bf16_f32 v171, v163, v167
	v_cvt_pk_bf16_f32 v172, v136, v161
	v_cvt_pk_bf16_f32 v173, v165, v169
	global_store_dwordx4 v[176:177], v[170:173], off offset:256
	v_mul_f32_e32 v134, 0xbfb8aa3b, v174
	v_exp_f32_e32 v134, v134
	v_mad_i64_i32 v[170:171], s[0:1], v132, s92, v[158:159]
	v_pk_mul_f32 v[180:181], v[90:91], v[168:169] op_sel_hi:[1,0]
	v_add_f32_e32 v132, 1.0, v134
	v_mul_f32_e32 v163, 0xbfb8aa3b, v180
	v_exp_f32_e32 v163, v163
	v_pk_mul_f32 v[172:173], v[96:97], v[168:169] op_sel_hi:[1,0]
	v_add_f32_e32 v157, 1.0, v163
	v_mul_f32_e32 v161, 0xbfb8aa3b, v175
	v_rcp_f32_e32 v132, v132
	v_exp_f32_e32 v161, v161
	s_nop 0
	v_add_f32_e32 v161, 1.0, v161
	v_mul_f32_e32 v165, 0xbfb8aa3b, v181
	v_exp_f32_e32 v165, v165
	v_rcp_f32_e32 v134, v157
	v_pk_mul_f32 v[176:177], v[92:93], v[168:169] op_sel_hi:[1,0]
	v_add_f32_e32 v163, 1.0, v165
	v_mul_f32_e32 v167, 0xbfb8aa3b, v172
	v_exp_f32_e32 v167, v167
	v_rcp_f32_e32 v136, v161
	v_add_f32_e32 v165, 1.0, v167
	v_mul_f32_e32 v169, 0xbfb8aa3b, v176
	v_exp_f32_e32 v169, v169
	v_rcp_f32_e32 v157, v163
	v_add_f32_e32 v167, 1.0, v169
	v_mul_f32_e32 v172, 0xbfb8aa3b, v173
	v_exp_f32_e32 v172, v172
	v_rcp_f32_e32 v161, v165
	v_add_f32_e32 v169, 1.0, v172
	v_mul_f32_e32 v174, 0xbfb8aa3b, v177
	v_exp_f32_e32 v174, v174
	v_rcp_f32_e32 v163, v167
	v_add_f32_e32 v172, 1.0, v174
	v_rcp_f32_e32 v165, v169
	v_pk_mul_f32 v[176:177], v[86:87], v[168:169] op_sel_hi:[1,0]
	v_lshl_add_u64 v[174:175], v[170:171], 0, v[148:149]
	v_cvt_pk_bf16_f32 v170, v132, v136
	v_mul_f32_e32 v132, 0xbfb8aa3b, v176
	v_exp_f32_e32 v132, v132
	v_rcp_f32_e32 v167, v172
	v_cvt_pk_bf16_f32 v172, v134, v157
	v_cvt_pk_bf16_f32 v171, v161, v165
	v_add_f32_e32 v132, 1.0, v132
	v_cvt_pk_bf16_f32 v173, v163, v167
	global_store_dwordx4 v[174:175], v[170:173], off
	s_nop 0
	s_nop 0
	v_pk_mul_f32 v[170:171], v[88:89], v[168:169] op_sel_hi:[1,0]
	v_pk_mul_f32 v[172:173], v[84:85], v[168:169] op_sel_hi:[1,0]
	v_pk_mul_f32 v[168:169], v[82:83], v[168:169] op_sel_hi:[1,0]
	v_mul_f32_e32 v163, 0xbfb8aa3b, v168
	v_exp_f32_e32 v163, v163
	s_nop 0
	v_add_f32_e32 v157, 1.0, v163
	v_mul_f32_e32 v161, 0xbfb8aa3b, v177
	v_rcp_f32_e32 v132, v132
	v_exp_f32_e32 v161, v161
	s_nop 0
	v_add_f32_e32 v161, 1.0, v161
	v_mul_f32_e32 v165, 0xbfb8aa3b, v169
	v_exp_f32_e32 v165, v165
	v_rcp_f32_e32 v134, v157
	v_add_f32_e32 v163, 1.0, v165
	v_mul_f32_e32 v167, 0xbfb8aa3b, v170
	v_exp_f32_e32 v167, v167
	v_rcp_f32_e32 v136, v161
	v_add_f32_e32 v165, 1.0, v167
	v_mul_f32_e32 v168, 0xbfb8aa3b, v172
	v_exp_f32_e32 v168, v168
	v_rcp_f32_e32 v157, v163
	v_add_f32_e32 v167, 1.0, v168
	v_mul_f32_e32 v169, 0xbfb8aa3b, v171
	v_exp_f32_e32 v169, v169
	v_rcp_f32_e32 v161, v165
	v_add_f32_e32 v168, 1.0, v169
	v_mul_f32_e32 v170, 0xbfb8aa3b, v173
	v_exp_f32_e32 v170, v170
	v_rcp_f32_e32 v163, v167
	v_add_f32_e32 v169, 1.0, v170
	v_rcp_f32_e32 v165, v168
	v_rcp_f32_e32 v167, v169
	s_nop 0
	v_pk_mul_f32 v[172:173], v[78:79], v[166:167] op_sel_hi:[1,0]
	v_cvt_pk_bf16_f32 v168, v132, v136
	v_cvt_pk_bf16_f32 v169, v161, v165
	v_cvt_pk_bf16_f32 v170, v134, v157
	v_cvt_pk_bf16_f32 v171, v163, v167
	global_store_dwordx4 v[174:175], v[168:171], off offset:256
	v_mul_f32_e32 v132, 0xbfb8aa3b, v172
	v_exp_f32_e32 v132, v132
	v_mad_i64_i32 v[168:169], s[0:1], v130, s92, v[158:159]
	v_pk_mul_f32 v[176:177], v[74:75], v[166:167] op_sel_hi:[1,0]
	v_add_f32_e32 v130, 1.0, v132
	v_mul_f32_e32 v161, 0xbfb8aa3b, v176
	v_exp_f32_e32 v161, v161
	v_pk_mul_f32 v[170:171], v[80:81], v[166:167] op_sel_hi:[1,0]
	v_add_f32_e32 v136, 1.0, v161
	v_mul_f32_e32 v157, 0xbfb8aa3b, v173
	v_rcp_f32_e32 v130, v130
	v_exp_f32_e32 v157, v157
	s_nop 0
	v_add_f32_e32 v157, 1.0, v157
	v_mul_f32_e32 v163, 0xbfb8aa3b, v177
	v_exp_f32_e32 v163, v163
	v_rcp_f32_e32 v132, v136
	v_pk_mul_f32 v[174:175], v[76:77], v[166:167] op_sel_hi:[1,0]
	v_add_f32_e32 v161, 1.0, v163
	v_mul_f32_e32 v165, 0xbfb8aa3b, v170
	v_exp_f32_e32 v165, v165
	v_rcp_f32_e32 v134, v157
	v_add_f32_e32 v163, 1.0, v165
	v_mul_f32_e32 v167, 0xbfb8aa3b, v174
	v_exp_f32_e32 v167, v167
	v_rcp_f32_e32 v136, v161
	v_add_f32_e32 v165, 1.0, v167
	v_mul_f32_e32 v170, 0xbfb8aa3b, v171
	v_exp_f32_e32 v170, v170
	v_rcp_f32_e32 v157, v163
	v_add_f32_e32 v167, 1.0, v170
	v_mul_f32_e32 v172, 0xbfb8aa3b, v175
	v_exp_f32_e32 v172, v172
	v_rcp_f32_e32 v161, v165
	v_add_f32_e32 v170, 1.0, v172
	v_rcp_f32_e32 v163, v167
	v_pk_mul_f32 v[174:175], v[70:71], v[166:167] op_sel_hi:[1,0]
	v_lshl_add_u64 v[172:173], v[168:169], 0, v[148:149]
	v_cvt_pk_bf16_f32 v168, v130, v134
	v_mul_f32_e32 v130, 0xbfb8aa3b, v174
	v_exp_f32_e32 v130, v130
	v_rcp_f32_e32 v165, v170
	v_cvt_pk_bf16_f32 v170, v132, v136
	v_cvt_pk_bf16_f32 v169, v157, v163
	v_add_f32_e32 v130, 1.0, v130
	v_cvt_pk_bf16_f32 v171, v161, v165
	global_store_dwordx4 v[172:173], v[168:171], off
	s_nop 0
	s_nop 0
	v_pk_mul_f32 v[168:169], v[72:73], v[166:167] op_sel_hi:[1,0]
	v_pk_mul_f32 v[170:171], v[68:69], v[166:167] op_sel_hi:[1,0]
	v_pk_mul_f32 v[166:167], v[66:67], v[166:167] op_sel_hi:[1,0]
	v_mul_f32_e32 v161, 0xbfb8aa3b, v166
	v_exp_f32_e32 v161, v161
	s_nop 0
	v_add_f32_e32 v136, 1.0, v161
	v_mul_f32_e32 v157, 0xbfb8aa3b, v175
	v_rcp_f32_e32 v130, v130
	v_exp_f32_e32 v157, v157
	s_nop 0
	v_add_f32_e32 v157, 1.0, v157
	v_mul_f32_e32 v163, 0xbfb8aa3b, v167
	v_exp_f32_e32 v163, v163
	v_rcp_f32_e32 v132, v136
	v_add_f32_e32 v161, 1.0, v163
	v_mul_f32_e32 v165, 0xbfb8aa3b, v168
	v_exp_f32_e32 v165, v165
	v_rcp_f32_e32 v134, v157
	v_add_f32_e32 v163, 1.0, v165
	v_mul_f32_e32 v166, 0xbfb8aa3b, v170
	v_exp_f32_e32 v166, v166
	v_rcp_f32_e32 v136, v161
	v_add_f32_e32 v165, 1.0, v166
	v_mul_f32_e32 v167, 0xbfb8aa3b, v169
	v_exp_f32_e32 v167, v167
	v_rcp_f32_e32 v157, v163
	v_add_f32_e32 v166, 1.0, v167
	v_mul_f32_e32 v168, 0xbfb8aa3b, v171
	v_exp_f32_e32 v168, v168
	v_rcp_f32_e32 v161, v165
	v_add_f32_e32 v167, 1.0, v168
	v_rcp_f32_e32 v163, v166
	v_rcp_f32_e32 v165, v167
	s_nop 0
	v_pk_mul_f32 v[170:171], v[62:63], v[164:165] op_sel_hi:[1,0]
	v_cvt_pk_bf16_f32 v166, v130, v134
	v_cvt_pk_bf16_f32 v168, v132, v136
	v_cvt_pk_bf16_f32 v167, v157, v163
	v_cvt_pk_bf16_f32 v169, v161, v165
	global_store_dwordx4 v[172:173], v[166:169], off offset:256
	v_mul_f32_e32 v130, 0xbfb8aa3b, v170
	v_exp_f32_e32 v130, v130
	v_pk_mul_f32 v[172:173], v[58:59], v[164:165] op_sel_hi:[1,0]
	v_pk_mul_f32 v[166:167], v[64:65], v[164:165] op_sel_hi:[1,0]
	v_mul_f32_e32 v163, 0xbfb8aa3b, v172
	v_add_f32_e32 v130, 1.0, v130
	v_exp_f32_e32 v163, v163
	v_pk_mul_f32 v[168:169], v[60:61], v[164:165] op_sel_hi:[1,0]
	v_mul_f32_e32 v166, 0xbfb8aa3b, v166
	v_add_f32_e32 v157, 1.0, v163
	v_mul_f32_e32 v161, 0xbfb8aa3b, v171
	v_rcp_f32_e32 v130, v130
	v_exp_f32_e32 v161, v161
	s_nop 0
	v_add_f32_e32 v161, 1.0, v161
	v_mul_f32_e32 v165, 0xbfb8aa3b, v173
	v_exp_f32_e32 v165, v165
	v_rcp_f32_e32 v132, v157
	v_add_f32_e32 v163, 1.0, v165
	v_exp_f32_e32 v166, v166
	v_rcp_f32_e32 v134, v161
	v_add_f32_e32 v165, 1.0, v166
	v_mul_f32_e32 v168, 0xbfb8aa3b, v168
	v_exp_f32_e32 v168, v168
	v_rcp_f32_e32 v157, v163
	v_add_f32_e32 v166, 1.0, v168
	v_mul_f32_e32 v167, 0xbfb8aa3b, v167
	v_exp_f32_e32 v167, v167
	v_rcp_f32_e32 v161, v165
	v_add_f32_e32 v167, 1.0, v167
	v_mul_f32_e32 v169, 0xbfb8aa3b, v169
	v_exp_f32_e32 v169, v169
	v_rcp_f32_e32 v163, v166
	v_add_f32_e32 v168, 1.0, v169
	v_rcp_f32_e32 v165, v167
	v_mad_i64_i32 v[136:137], s[0:1], v137, s92, v[158:159]
	v_pk_mul_f32 v[170:171], v[54:55], v[164:165] op_sel_hi:[1,0]
	v_rcp_f32_e32 v169, v168
	v_cvt_pk_bf16_f32 v166, v130, v134
	v_mul_f32_e32 v130, 0xbfb8aa3b, v170
	v_exp_f32_e32 v130, v130
	v_cvt_pk_bf16_f32 v168, v132, v157
	v_lshl_add_u64 v[136:137], v[136:137], 0, v[148:149]
	v_cvt_pk_bf16_f32 v167, v161, v165
	v_add_f32_e32 v130, 1.0, v130
	v_cvt_pk_bf16_f32 v169, v163, v169
	global_store_dwordx4 v[136:137], v[166:169], off
	s_nop 0
	s_nop 0
	v_pk_mul_f32 v[166:167], v[56:57], v[164:165] op_sel_hi:[1,0]
	v_pk_mul_f32 v[168:169], v[52:53], v[164:165] op_sel_hi:[1,0]
	v_pk_mul_f32 v[164:165], v[50:51], v[164:165] op_sel_hi:[1,0]
	v_mul_f32_e32 v163, 0xbfb8aa3b, v164
	v_exp_f32_e32 v163, v163
	s_nop 0
	v_add_f32_e32 v157, 1.0, v163
	v_mul_f32_e32 v161, 0xbfb8aa3b, v171
	v_rcp_f32_e32 v130, v130
	v_exp_f32_e32 v161, v161
	s_nop 0
	v_add_f32_e32 v161, 1.0, v161
	v_mul_f32_e32 v164, 0xbfb8aa3b, v165
	v_exp_f32_e32 v164, v164
	v_rcp_f32_e32 v132, v157
	v_add_f32_e32 v163, 1.0, v164
	v_mul_f32_e32 v166, 0xbfb8aa3b, v166
	v_exp_f32_e32 v166, v166
	v_rcp_f32_e32 v134, v161
	v_add_f32_e32 v164, 1.0, v166
	v_mul_f32_e32 v165, 0xbfb8aa3b, v168
	v_exp_f32_e32 v165, v165
	v_rcp_f32_e32 v157, v163
	v_add_f32_e32 v165, 1.0, v165
	v_mul_f32_e32 v167, 0xbfb8aa3b, v167
	v_exp_f32_e32 v167, v167
	v_rcp_f32_e32 v161, v164
	v_add_f32_e32 v166, 1.0, v167
	v_mul_f32_e32 v168, 0xbfb8aa3b, v169
	v_exp_f32_e32 v168, v168
	v_rcp_f32_e32 v163, v165
	v_add_f32_e32 v167, 1.0, v168
	v_rcp_f32_e32 v165, v166
	s_nop 0
	v_cvt_pk_bf16_f32 v165, v161, v165
	v_pk_mul_f32 v[168:169], v[46:47], v[162:163] op_sel_hi:[1,0]
	v_rcp_f32_e32 v167, v167
	v_cvt_pk_bf16_f32 v164, v130, v134
	v_mul_f32_e32 v130, 0xbfb8aa3b, v168
	v_exp_f32_e32 v130, v130
	v_cvt_pk_bf16_f32 v166, v132, v157
	v_cvt_pk_bf16_f32 v167, v163, v167
	global_store_dwordx4 v[136:137], v[164:167], off offset:256
	s_nop 0
	v_add_f32_e32 v130, 1.0, v130
	v_pk_mul_f32 v[166:167], v[42:43], v[162:163] op_sel_hi:[1,0]
	v_pk_mul_f32 v[136:137], v[48:49], v[162:163] op_sel_hi:[1,0]
	v_mul_f32_e32 v166, 0xbfb8aa3b, v166
	v_exp_f32_e32 v166, v166
	v_pk_mul_f32 v[164:165], v[44:45], v[162:163] op_sel_hi:[1,0]
	v_add_f32_e32 v161, 1.0, v166
	v_mul_f32_e32 v163, 0xbfb8aa3b, v169
	v_rcp_f32_e32 v130, v130
	v_exp_f32_e32 v163, v163
	s_nop 0
	v_add_f32_e32 v163, 1.0, v163
	v_mul_f32_e32 v167, 0xbfb8aa3b, v167
	v_exp_f32_e32 v167, v167
	v_rcp_f32_e32 v132, v161
	v_add_f32_e32 v166, 1.0, v167
	v_mul_f32_e32 v136, 0xbfb8aa3b, v136
	v_exp_f32_e32 v136, v136
	v_rcp_f32_e32 v157, v163
	v_add_f32_e32 v136, 1.0, v136
	v_mul_f32_e32 v164, 0xbfb8aa3b, v164
	v_exp_f32_e32 v164, v164
	v_rcp_f32_e32 v161, v166
	v_add_f32_e32 v164, 1.0, v164
	v_mul_f32_e32 v137, 0xbfb8aa3b, v137
	v_rcp_f32_e32 v136, v136
	v_exp_f32_e32 v137, v137
	s_nop 0
	v_add_f32_e32 v137, 1.0, v137
	v_mul_f32_e32 v165, 0xbfb8aa3b, v165
	v_rcp_f32_e32 v163, v164
	v_exp_f32_e32 v165, v165
	s_nop 0
	v_add_f32_e32 v165, 1.0, v165
	v_rcp_f32_e32 v137, v137
	v_mad_i64_i32 v[134:135], s[0:1], v135, s92, v[158:159]
	v_pk_mul_f32 v[166:167], v[38:39], v[162:163] op_sel_hi:[1,0]
	v_rcp_f32_e32 v168, v165
	v_lshl_add_u64 v[164:165], v[134:135], 0, v[148:149]
	v_cvt_pk_bf16_f32 v134, v130, v157
	v_mul_f32_e32 v130, 0xbfb8aa3b, v166
	v_exp_f32_e32 v130, v130
	v_cvt_pk_bf16_f32 v135, v136, v137
	v_cvt_pk_bf16_f32 v136, v132, v161
	v_cvt_pk_bf16_f32 v137, v163, v168
	global_store_dwordx4 v[164:165], v[134:137], off
	s_nop 0
	v_add_f32_e32 v130, 1.0, v130
	v_pk_mul_f32 v[134:135], v[40:41], v[162:163] op_sel_hi:[1,0]
	v_pk_mul_f32 v[136:137], v[36:37], v[162:163] op_sel_hi:[1,0]
	v_pk_mul_f32 v[162:163], v[34:35], v[162:163] op_sel_hi:[1,0]
	v_mul_f32_e32 v162, 0xbfb8aa3b, v162
	v_exp_f32_e32 v162, v162
	s_nop 0
	v_add_f32_e32 v161, 1.0, v162
	v_rcp_f32_e32 v130, v130
	v_mul_f32_e32 v166, 0xbfb8aa3b, v167
	v_exp_f32_e32 v166, v166
	s_nop 0
	v_add_f32_e32 v162, 1.0, v166
	v_mul_f32_e32 v163, 0xbfb8aa3b, v163
	v_exp_f32_e32 v163, v163
	v_rcp_f32_e32 v132, v161
	v_add_f32_e32 v163, 1.0, v163
	v_mul_f32_e32 v134, 0xbfb8aa3b, v134
	v_exp_f32_e32 v134, v134
	v_rcp_f32_e32 v157, v162
	v_add_f32_e32 v134, 1.0, v134
	v_mul_f32_e32 v136, 0xbfb8aa3b, v136
	v_exp_f32_e32 v136, v136
	v_rcp_f32_e32 v161, v163
	v_add_f32_e32 v136, 1.0, v136
	v_mul_f32_e32 v135, 0xbfb8aa3b, v135
	v_rcp_f32_e32 v162, v134
	v_exp_f32_e32 v135, v135
	s_nop 0
	v_add_f32_e32 v135, 1.0, v135
	v_mul_f32_e32 v137, 0xbfb8aa3b, v137
	v_rcp_f32_e32 v163, v136
	v_exp_f32_e32 v137, v137
	s_nop 0
	v_add_f32_e32 v137, 1.0, v137
	v_rcp_f32_e32 v135, v135
	s_nop 0
	v_cvt_pk_bf16_f32 v135, v162, v135
	v_rcp_f32_e32 v137, v137
	s_nop 0
	v_cvt_pk_bf16_f32 v137, v163, v137
	v_pk_mul_f32 v[162:163], v[30:31], v[160:161] op_sel_hi:[1,0]
	v_cvt_pk_bf16_f32 v134, v130, v157
	v_cvt_pk_bf16_f32 v136, v132, v161
	global_store_dwordx4 v[164:165], v[134:137], off offset:256
	v_mul_f32_e32 v130, 0xbfb8aa3b, v162
	v_exp_f32_e32 v130, v130
	v_mul_f32_e32 v163, 0xbfb8aa3b, v163
	v_exp_f32_e32 v163, v163
	v_mad_i64_i32 v[132:133], s[0:1], v133, s92, v[158:159]
	v_add_f32_e32 v130, 1.0, v130
	v_add_f32_e32 v163, 1.0, v163
	v_pk_mul_f32 v[164:165], v[26:27], v[160:161] op_sel_hi:[1,0]
	v_mul_f32_e32 v164, 0xbfb8aa3b, v164
	v_pk_mul_f32 v[134:135], v[32:33], v[160:161] op_sel_hi:[1,0]
	v_pk_mul_f32 v[136:137], v[28:29], v[160:161] op_sel_hi:[1,0]
	v_exp_f32_e32 v164, v164
	s_nop 0
	v_add_f32_e32 v162, 1.0, v164
	v_rcp_f32_e32 v130, v130
	v_mul_f32_e32 v165, 0xbfb8aa3b, v165
	v_exp_f32_e32 v165, v165
	v_rcp_f32_e32 v157, v162
	v_add_f32_e32 v164, 1.0, v165
	v_mul_f32_e32 v134, 0xbfb8aa3b, v134
	v_exp_f32_e32 v134, v134
	v_rcp_f32_e32 v161, v163
	v_add_f32_e32 v134, 1.0, v134
	v_mul_f32_e32 v136, 0xbfb8aa3b, v136
	v_rcp_f32_e32 v164, v164
	v_exp_f32_e32 v136, v136
	s_nop 0
	v_add_f32_e32 v136, 1.0, v136
	v_mul_f32_e32 v135, 0xbfb8aa3b, v135
	v_rcp_f32_e32 v134, v134
	v_exp_f32_e32 v135, v135
	s_nop 0
	v_add_f32_e32 v135, 1.0, v135
	v_mul_f32_e32 v137, 0xbfb8aa3b, v137
	v_exp_f32_e32 v137, v137
	v_rcp_f32_e32 v167, v136
	v_add_f32_e32 v137, 1.0, v137
	v_rcp_f32_e32 v135, v135
	v_pk_mul_f32 v[162:163], v[22:23], v[160:161] op_sel_hi:[1,0]
	v_rcp_f32_e32 v165, v137
	v_lshl_add_u64 v[136:137], v[132:133], 0, v[148:149]
	v_cvt_pk_bf16_f32 v132, v130, v161
	v_mul_f32_e32 v130, 0xbfb8aa3b, v162
	v_exp_f32_e32 v130, v130
	v_cvt_pk_bf16_f32 v133, v134, v135
	v_cvt_pk_bf16_f32 v134, v157, v164
	v_cvt_pk_bf16_f32 v135, v167, v165
	global_store_dwordx4 v[136:137], v[132:135], off
	s_nop 0
	v_add_f32_e32 v130, 1.0, v130
	v_pk_mul_f32 v[132:133], v[24:25], v[160:161] op_sel_hi:[1,0]
	v_pk_mul_f32 v[134:135], v[20:21], v[160:161] op_sel_hi:[1,0]
	v_pk_mul_f32 v[160:161], v[18:19], v[160:161] op_sel_hi:[1,0]
	v_mul_f32_e32 v160, 0xbfb8aa3b, v160
	v_exp_f32_e32 v160, v160
	s_nop 0
	v_add_f32_e32 v160, 1.0, v160
	v_mul_f32_e32 v163, 0xbfb8aa3b, v163
	v_rcp_f32_e32 v130, v130
	v_exp_f32_e32 v163, v163
	s_nop 0
	v_add_f32_e32 v163, 1.0, v163
	v_mul_f32_e32 v161, 0xbfb8aa3b, v161
	v_rcp_f32_e32 v157, v160
	v_exp_f32_e32 v161, v161
	s_nop 0
	v_add_f32_e32 v161, 1.0, v161
	v_mul_f32_e32 v132, 0xbfb8aa3b, v132
	v_exp_f32_e32 v132, v132
	v_rcp_f32_e32 v160, v163
	v_add_f32_e32 v132, 1.0, v132
	v_mul_f32_e32 v134, 0xbfb8aa3b, v134
	v_rcp_f32_e32 v161, v161
	v_exp_f32_e32 v134, v134
	s_nop 0
	v_add_f32_e32 v134, 1.0, v134
	v_mul_f32_e32 v133, 0xbfb8aa3b, v133
	v_rcp_f32_e32 v162, v132
	v_exp_f32_e32 v133, v133
	s_nop 0
	v_add_f32_e32 v133, 1.0, v133
	v_mul_f32_e32 v135, 0xbfb8aa3b, v135
	v_rcp_f32_e32 v163, v134
	v_exp_f32_e32 v135, v135
	s_nop 0
	v_add_f32_e32 v135, 1.0, v135
	v_rcp_f32_e32 v133, v133
	s_nop 0
	v_cvt_pk_bf16_f32 v133, v162, v133
	v_rcp_f32_e32 v135, v135
	v_cvt_pk_bf16_f32 v132, v130, v160
	v_cvt_pk_bf16_f32 v134, v157, v161
	v_pk_mul_f32 v[160:161], v[14:15], v[156:157] op_sel_hi:[1,0]
	v_cvt_pk_bf16_f32 v135, v163, v135
	global_store_dwordx4 v[136:137], v[132:135], off offset:256
	v_mul_f32_e32 v130, 0xbfb8aa3b, v160
	v_exp_f32_e32 v157, v130
	v_mad_i64_i32 v[130:131], s[0:1], v131, s92, v[158:159]
	v_mul_f32_e32 v161, 0xbfb8aa3b, v161
	v_add_f32_e32 v157, 1.0, v157
	v_pk_mul_f32 v[136:137], v[10:11], v[156:157] op_sel_hi:[1,0]
	v_pk_mul_f32 v[132:133], v[16:17], v[156:157] op_sel_hi:[1,0]
	v_mul_f32_e32 v136, 0xbfb8aa3b, v136
	v_exp_f32_e32 v136, v136
	s_nop 0
	v_add_f32_e32 v136, 1.0, v136
	v_pk_mul_f32 v[134:135], v[12:13], v[156:157] op_sel_hi:[1,0]
	v_rcp_f32_e32 v157, v157
	v_exp_f32_e32 v161, v161
	s_nop 0
	v_add_f32_e32 v160, 1.0, v161
	v_mul_f32_e32 v137, 0xbfb8aa3b, v137
	v_rcp_f32_e32 v158, v136
	v_exp_f32_e32 v137, v137
	s_nop 0
	v_add_f32_e32 v137, 1.0, v137
	v_mul_f32_e32 v132, 0xbfb8aa3b, v132
	v_exp_f32_e32 v132, v132
	v_rcp_f32_e32 v136, v160
	v_add_f32_e32 v132, 1.0, v132
	v_mul_f32_e32 v134, 0xbfb8aa3b, v134
	v_rcp_f32_e32 v159, v137
	v_exp_f32_e32 v134, v134
	s_nop 0
	v_add_f32_e32 v134, 1.0, v134
	v_mul_f32_e32 v133, 0xbfb8aa3b, v133
	v_rcp_f32_e32 v132, v132
	v_exp_f32_e32 v133, v133
	s_nop 0
	v_add_f32_e32 v133, 1.0, v133
	v_mul_f32_e32 v135, 0xbfb8aa3b, v135
	v_rcp_f32_e32 v160, v134
	v_exp_f32_e32 v135, v135
	s_nop 0
	v_add_f32_e32 v135, 1.0, v135
	v_rcp_f32_e32 v133, v133
	v_rcp_f32_e32 v161, v135
	v_lshl_add_u64 v[134:135], v[130:131], 0, v[148:149]
	v_cvt_pk_bf16_f32 v130, v157, v136
	v_pk_mul_f32 v[136:137], v[6:7], v[156:157] op_sel_hi:[1,0]
	v_cvt_pk_bf16_f32 v131, v132, v133
	v_cvt_pk_bf16_f32 v133, v160, v161
	s_nop 0
	v_mul_f32_e32 v132, 0xbfb8aa3b, v136
	v_exp_f32_e32 v136, v132
	v_cvt_pk_bf16_f32 v132, v158, v159
	global_store_dwordx4 v[134:135], v[130:133], off
	v_mul_f32_e32 v137, 0xbfb8aa3b, v137
	v_add_f32_e32 v136, 1.0, v136
	v_pk_mul_f32 v[130:131], v[8:9], v[156:157] op_sel_hi:[1,0]
	v_pk_mul_f32 v[132:133], v[4:5], v[156:157] op_sel_hi:[1,0]
	v_pk_mul_f32 v[156:157], v[2:3], v[156:157] op_sel_hi:[1,0]
	v_mul_f32_e32 v156, 0xbfb8aa3b, v156
	v_exp_f32_e32 v156, v156
	s_nop 0
	v_add_f32_e32 v156, 1.0, v156
	v_rcp_f32_e32 v136, v136
	v_exp_f32_e32 v137, v137
	s_nop 0
	v_add_f32_e32 v137, 1.0, v137
	v_mul_f32_e32 v157, 0xbfb8aa3b, v157
	v_rcp_f32_e32 v148, v156
	v_exp_f32_e32 v157, v157
	s_nop 0
	v_add_f32_e32 v157, 1.0, v157
	v_mul_f32_e32 v130, 0xbfb8aa3b, v130
	v_rcp_f32_e32 v137, v137
	v_exp_f32_e32 v130, v130
	s_nop 0
	v_add_f32_e32 v130, 1.0, v130
	v_mul_f32_e32 v132, 0xbfb8aa3b, v132
	v_rcp_f32_e32 v156, v157
	v_exp_f32_e32 v132, v132
	s_nop 0
	v_add_f32_e32 v132, 1.0, v132
	v_mul_f32_e32 v131, 0xbfb8aa3b, v131
	v_rcp_f32_e32 v157, v130
	v_exp_f32_e32 v131, v131
	s_nop 0
	v_add_f32_e32 v131, 1.0, v131
	v_mul_f32_e32 v133, 0xbfb8aa3b, v133
	v_rcp_f32_e32 v158, v132
	v_exp_f32_e32 v133, v133
	s_nop 0
	v_add_f32_e32 v133, 1.0, v133
	v_rcp_f32_e32 v131, v131
	s_nop 0
	v_cvt_pk_bf16_f32 v131, v157, v131
	v_rcp_f32_e32 v133, v133
	v_cvt_pk_bf16_f32 v130, v136, v137
	v_cvt_pk_bf16_f32 v132, v148, v156
	v_cvt_pk_bf16_f32 v133, v158, v133
	global_store_dwordx4 v[134:135], v[130:133], off offset:256

.LBB0_550:
	v_lshl_add_u32 v130, s70, 8, v187
	v_ashrrev_i32_e32 v131, 31, v130
	v_lshl_add_u64 v[172:173], v[130:131], 2, s[22:23]
	global_load_dword v168, v[172:173], off
	v_or_b32_e32 v166, 16, v130
	v_or_b32_e32 v158, 48, v130
	v_or_b32_e32 v162, 32, v130
	v_ashrrev_i32_e32 v167, 31, v166
	v_ashrrev_i32_e32 v159, 31, v158
	v_mov_b64_e32 v[132:133], s[34:35]
	v_ashrrev_i32_e32 v163, 31, v162
	v_lshl_add_u64 v[160:161], v[166:167], 2, s[22:23]
	v_lshl_add_u64 v[180:181], v[158:159], 2, s[22:23]
	v_add_u32_e32 v157, 0x80, v130
	v_add_u32_e32 v137, 0x90, v130
	v_add_u32_e32 v135, 0xa0, v130
	v_add_u32_e32 v131, 0xb0, v130
	v_mad_i64_i32 v[174:175], s[0:1], v130, s92, v[132:133]
	v_lshl_add_u64 v[176:177], v[162:163], 2, s[22:23]
	global_load_dword v148, v[172:173], off offset:512
	global_load_dword v136, v[172:173], off offset:576
	global_load_dword v134, v[172:173], off offset:640
	global_load_dword v164, v[160:161], off
	s_nop 0
	global_load_dword v160, v[176:177], off
	global_load_dword v156, v[180:181], off
	global_load_dword v130, v[172:173], off offset:704
	v_lshl_or_b32 v170, s68, 8, v189
	s_waitcnt vmcnt(0)
	v_pk_mul_f32 v[126:127], v[126:127], v[168:169] op_sel_hi:[1,0]
	v_pk_mul_f32 v[122:123], v[122:123], v[168:169] op_sel_hi:[1,0]
	v_mul_f32_e32 v159, 0xbfb8aa3b, v126
	v_mul_f32_e32 v161, 0xbfb8aa3b, v122
	v_exp_f32_e32 v159, v159
	v_mul_f32_e32 v163, 0xbfb8aa3b, v127
	v_exp_f32_e32 v161, v161
	v_exp_f32_e32 v163, v163
	v_mul_f32_e32 v165, 0xbfb8aa3b, v123
	v_exp_f32_e32 v165, v165
	v_add_f32_e32 v159, 1.0, v159
	v_pk_mul_f32 v[128:129], v[128:129], v[168:169] op_sel_hi:[1,0]
	v_pk_mul_f32 v[124:125], v[124:125], v[168:169] op_sel_hi:[1,0]
	v_add_f32_e32 v161, 1.0, v161
	v_add_f32_e32 v163, 1.0, v163
	v_add_f32_e32 v165, 1.0, v165
	v_mul_f32_e32 v167, 0xbfb8aa3b, v128
	v_exp_f32_e32 v167, v167
	s_nop 0
	v_add_f32_e32 v167, 1.0, v167
	v_rcp_f32_e32 v169, v159
	s_nop 0
	v_mul_f32_e32 v126, v126, v169
	v_rcp_f32_e32 v159, v161
	s_nop 0
	v_mul_f32_e32 v159, v122, v159
	v_rcp_f32_e32 v122, v163
	s_nop 0
	v_mul_f32_e32 v127, v127, v122
	v_mul_f32_e32 v163, 0xbfb8aa3b, v124
	v_exp_f32_e32 v163, v163
	v_rcp_f32_e32 v122, v165
	s_nop 0
	v_mul_f32_e32 v161, v123, v122
	v_add_f32_e32 v163, 1.0, v163
	v_rcp_f32_e32 v122, v167
	s_nop 0
	v_mul_f32_e32 v167, v128, v122
	v_mul_f32_e32 v128, 0xbfb8aa3b, v129
	v_exp_f32_e32 v128, v128
	s_nop 0
	v_add_f32_e32 v128, 1.0, v128
	v_rcp_f32_e32 v122, v163
	s_nop 0
	v_mul_f32_e32 v163, v124, v122
	v_mul_f32_e32 v124, 0xbfb8aa3b, v125
	v_exp_f32_e32 v124, v124
	s_nop 0
	v_add_f32_e32 v124, 1.0, v124
	v_rcp_f32_e32 v122, v128
	s_nop 0
	v_mul_f32_e32 v172, v129, v122
	v_ashrrev_i32_e32 v171, 31, v170
	v_pk_mul_f32 v[118:119], v[118:119], v[168:169] op_sel_hi:[1,0]
	v_rcp_f32_e32 v122, v124
	s_nop 0
	v_mul_f32_e32 v165, v125, v122
	v_cvt_pk_bf16_f32 v124, v126, v127
	v_mul_f32_e32 v126, 0xbfb8aa3b, v118
	v_cvt_pk_bf16_f32 v125, v167, v172
	v_exp_f32_e32 v167, v126
	v_lshlrev_b64 v[122:123], 1, v[170:171]
	v_lshl_add_u64 v[128:129], v[174:175], 0, v[122:123]
	v_cvt_pk_bf16_f32 v126, v159, v161
	v_cvt_pk_bf16_f32 v127, v163, v165
	global_store_dwordx4 v[128:129], v[124:127], off
	v_pk_mul_f32 v[114:115], v[114:115], v[168:169] op_sel_hi:[1,0]
	v_pk_mul_f32 v[120:121], v[120:121], v[168:169] op_sel_hi:[1,0]
	v_add_f32_e32 v124, 1.0, v167
	v_mul_f32_e32 v161, 0xbfb8aa3b, v114
	v_exp_f32_e32 v161, v161
	v_pk_mul_f32 v[116:117], v[116:117], v[168:169] op_sel_hi:[1,0]
	v_add_f32_e32 v127, 1.0, v161
	v_mul_f32_e32 v126, 0xbfb8aa3b, v119
	v_exp_f32_e32 v126, v126
	v_rcp_f32_e32 v125, v124
	s_nop 0
	v_mul_f32_e32 v118, v118, v125
	v_add_f32_e32 v126, 1.0, v126
	v_rcp_f32_e32 v124, v127
	s_nop 0
	v_mul_f32_e32 v124, v114, v124
	v_mul_f32_e32 v127, 0xbfb8aa3b, v115
	v_exp_f32_e32 v127, v127
	s_nop 0
	v_add_f32_e32 v127, 1.0, v127
	v_rcp_f32_e32 v114, v126
	s_nop 0
	v_mul_f32_e32 v114, v119, v114
	v_mul_f32_e32 v126, 0xbfb8aa3b, v120
	v_exp_f32_e32 v126, v126
	s_nop 0
	v_add_f32_e32 v126, 1.0, v126
	v_rcp_f32_e32 v119, v127
	s_nop 0
	v_mul_f32_e32 v119, v115, v119
	v_mul_f32_e32 v127, 0xbfb8aa3b, v116
	v_exp_f32_e32 v127, v127
	s_nop 0
	v_add_f32_e32 v127, 1.0, v127
	v_rcp_f32_e32 v115, v126
	s_nop 0
	v_mul_f32_e32 v115, v120, v115
	v_mul_f32_e32 v126, 0xbfb8aa3b, v121
	v_exp_f32_e32 v126, v126
	s_nop 0
	v_add_f32_e32 v126, 1.0, v126
	v_rcp_f32_e32 v120, v127
	s_nop 0
	v_mul_f32_e32 v120, v116, v120
	v_mul_f32_e32 v127, 0xbfb8aa3b, v117
	v_exp_f32_e32 v127, v127
	s_nop 0
	v_add_f32_e32 v127, 1.0, v127
	v_rcp_f32_e32 v116, v126
	s_nop 0
	v_mul_f32_e32 v116, v121, v116
	v_pk_mul_f32 v[110:111], v[110:111], v[164:165] op_sel_hi:[1,0]
	v_cvt_pk_bf16_f32 v114, v118, v114
	v_mul_f32_e32 v118, 0xbfb8aa3b, v110
	v_exp_f32_e32 v118, v118
	v_rcp_f32_e32 v121, v127
	s_nop 0
	v_mul_f32_e32 v117, v117, v121
	v_cvt_pk_bf16_f32 v115, v115, v116
	v_cvt_pk_bf16_f32 v116, v124, v119
	v_cvt_pk_bf16_f32 v117, v120, v117
	global_store_dwordx4 v[128:129], v[114:117], off offset:256
	v_pk_mul_f32 v[106:107], v[106:107], v[164:165] op_sel_hi:[1,0]
	v_pk_mul_f32 v[112:113], v[112:113], v[164:165] op_sel_hi:[1,0]
	v_add_f32_e32 v116, 1.0, v118
	v_mul_f32_e32 v121, 0xbfb8aa3b, v106
	v_exp_f32_e32 v121, v121
	v_pk_mul_f32 v[108:109], v[108:109], v[164:165] op_sel_hi:[1,0]
	v_add_f32_e32 v119, 1.0, v121
	v_mul_f32_e32 v118, 0xbfb8aa3b, v111
	v_exp_f32_e32 v118, v118
	v_rcp_f32_e32 v117, v116
	s_nop 0
	v_mul_f32_e32 v116, v110, v117
	v_add_f32_e32 v118, 1.0, v118
	v_rcp_f32_e32 v110, v119
	s_nop 0
	v_mul_f32_e32 v117, v106, v110
	v_mul_f32_e32 v119, 0xbfb8aa3b, v107
	v_exp_f32_e32 v119, v119
	s_nop 0
	v_add_f32_e32 v119, 1.0, v119
	v_rcp_f32_e32 v106, v118
	s_nop 0
	v_mul_f32_e32 v106, v111, v106
	v_mul_f32_e32 v118, 0xbfb8aa3b, v112
	v_exp_f32_e32 v118, v118
	s_nop 0
	v_add_f32_e32 v118, 1.0, v118
	v_mul_f32_e32 v111, 0xbfb8aa3b, v108
	v_rcp_f32_e32 v110, v119
	s_nop 0
	v_mul_f32_e32 v119, v107, v110
	v_exp_f32_e32 v111, v111
	s_nop 0
	v_add_f32_e32 v111, 1.0, v111
	v_rcp_f32_e32 v107, v118
	s_nop 0
	v_mul_f32_e32 v107, v112, v107
	v_mul_f32_e32 v118, 0xbfb8aa3b, v113
	v_exp_f32_e32 v118, v118
	s_nop 0
	v_add_f32_e32 v118, 1.0, v118
	v_rcp_f32_e32 v110, v111
	s_nop 0
	v_mul_f32_e32 v112, v108, v110
	v_mul_f32_e32 v111, 0xbfb8aa3b, v109
	v_exp_f32_e32 v111, v111
	s_nop 0
	v_add_f32_e32 v111, 1.0, v111
	v_rcp_f32_e32 v108, v118
	s_nop 0
	v_mul_f32_e32 v108, v113, v108
	v_pk_mul_f32 v[102:103], v[102:103], v[164:165] op_sel_hi:[1,0]
	v_cvt_pk_bf16_f32 v107, v107, v108
	v_mul_f32_e32 v108, 0xbfb8aa3b, v102
	v_exp_f32_e32 v113, v108
	v_mad_i64_i32 v[114:115], s[0:1], v166, s92, v[132:133]
	v_rcp_f32_e32 v110, v111
	s_nop 0
	v_mul_f32_e32 v109, v109, v110
	v_lshl_add_u64 v[110:111], v[114:115], 0, v[122:123]
	v_cvt_pk_bf16_f32 v106, v116, v106
	v_cvt_pk_bf16_f32 v108, v117, v119
	v_cvt_pk_bf16_f32 v109, v112, v109
	global_store_dwordx4 v[110:111], v[106:109], off
	v_pk_mul_f32 v[98:99], v[98:99], v[164:165] op_sel_hi:[1,0]
	v_pk_mul_f32 v[104:105], v[104:105], v[164:165] op_sel_hi:[1,0]
	v_add_f32_e32 v106, 1.0, v113
	v_mul_f32_e32 v113, 0xbfb8aa3b, v98
	v_exp_f32_e32 v113, v113
	v_pk_mul_f32 v[100:101], v[100:101], v[164:165] op_sel_hi:[1,0]
	v_add_f32_e32 v109, 1.0, v113
	v_mul_f32_e32 v108, 0xbfb8aa3b, v103
	v_exp_f32_e32 v108, v108
	v_rcp_f32_e32 v107, v106
	s_nop 0
	v_mul_f32_e32 v102, v102, v107
	v_add_f32_e32 v108, 1.0, v108
	v_rcp_f32_e32 v106, v109
	s_nop 0
	v_mul_f32_e32 v106, v98, v106
	v_mul_f32_e32 v109, 0xbfb8aa3b, v99
	v_exp_f32_e32 v109, v109
	s_nop 0
	v_add_f32_e32 v109, 1.0, v109
	v_rcp_f32_e32 v98, v108
	s_nop 0
	v_mul_f32_e32 v98, v103, v98
	v_mul_f32_e32 v108, 0xbfb8aa3b, v104
	v_exp_f32_e32 v108, v108
	s_nop 0
	v_add_f32_e32 v108, 1.0, v108
	v_rcp_f32_e32 v103, v109
	s_nop 0
	v_mul_f32_e32 v103, v99, v103
	v_mul_f32_e32 v109, 0xbfb8aa3b, v100
	v_exp_f32_e32 v109, v109
	s_nop 0
	v_add_f32_e32 v109, 1.0, v109
	v_rcp_f32_e32 v99, v108
	s_nop 0
	v_mul_f32_e32 v99, v104, v99
	v_mul_f32_e32 v108, 0xbfb8aa3b, v105
	v_exp_f32_e32 v108, v108
	s_nop 0
	v_add_f32_e32 v108, 1.0, v108
	v_rcp_f32_e32 v104, v109
	s_nop 0
	v_mul_f32_e32 v104, v100, v104
	v_mul_f32_e32 v109, 0xbfb8aa3b, v101
	v_exp_f32_e32 v109, v109
	s_nop 0
	v_add_f32_e32 v109, 1.0, v109
	v_rcp_f32_e32 v100, v108
	s_nop 0
	v_mul_f32_e32 v100, v105, v100
	v_pk_mul_f32 v[94:95], v[94:95], v[160:161] op_sel_hi:[1,0]
	v_cvt_pk_bf16_f32 v98, v102, v98
	v_mul_f32_e32 v102, 0xbfb8aa3b, v94
	v_exp_f32_e32 v102, v102
	v_rcp_f32_e32 v105, v109
	s_nop 0
	v_mul_f32_e32 v101, v101, v105
	v_cvt_pk_bf16_f32 v99, v99, v100
	v_cvt_pk_bf16_f32 v100, v106, v103
	v_cvt_pk_bf16_f32 v101, v104, v101
	global_store_dwordx4 v[110:111], v[98:101], off offset:256
	v_pk_mul_f32 v[90:91], v[90:91], v[160:161] op_sel_hi:[1,0]
	v_pk_mul_f32 v[96:97], v[96:97], v[160:161] op_sel_hi:[1,0]
	v_add_f32_e32 v100, 1.0, v102
	v_mul_f32_e32 v105, 0xbfb8aa3b, v90
	v_exp_f32_e32 v105, v105
	v_pk_mul_f32 v[92:93], v[92:93], v[160:161] op_sel_hi:[1,0]
	v_add_f32_e32 v103, 1.0, v105
	v_mul_f32_e32 v102, 0xbfb8aa3b, v95
	v_exp_f32_e32 v102, v102
	v_rcp_f32_e32 v101, v100
	s_nop 0
	v_mul_f32_e32 v100, v94, v101
	v_add_f32_e32 v102, 1.0, v102
	v_rcp_f32_e32 v94, v103
	s_nop 0
	v_mul_f32_e32 v101, v90, v94
	v_mul_f32_e32 v103, 0xbfb8aa3b, v91
	v_exp_f32_e32 v103, v103
	s_nop 0
	v_add_f32_e32 v103, 1.0, v103
	v_rcp_f32_e32 v90, v102
	s_nop 0
	v_mul_f32_e32 v90, v95, v90
	v_mul_f32_e32 v102, 0xbfb8aa3b, v96
	v_exp_f32_e32 v102, v102
	s_nop 0
	v_add_f32_e32 v102, 1.0, v102
	v_mul_f32_e32 v95, 0xbfb8aa3b, v92
	v_rcp_f32_e32 v94, v103
	s_nop 0
	v_mul_f32_e32 v103, v91, v94
	v_exp_f32_e32 v95, v95
	s_nop 0
	v_add_f32_e32 v95, 1.0, v95
	v_rcp_f32_e32 v91, v102
	s_nop 0
	v_mul_f32_e32 v91, v96, v91
	v_mul_f32_e32 v102, 0xbfb8aa3b, v97
	v_exp_f32_e32 v102, v102
	s_nop 0
	v_add_f32_e32 v102, 1.0, v102
	v_rcp_f32_e32 v94, v95
	s_nop 0
	v_mul_f32_e32 v96, v92, v94
	v_mul_f32_e32 v95, 0xbfb8aa3b, v93
	v_exp_f32_e32 v95, v95
	s_nop 0
	v_add_f32_e32 v95, 1.0, v95
	v_rcp_f32_e32 v92, v102
	s_nop 0
	v_mul_f32_e32 v92, v97, v92
	v_pk_mul_f32 v[86:87], v[86:87], v[160:161] op_sel_hi:[1,0]
	v_cvt_pk_bf16_f32 v91, v91, v92
	v_mul_f32_e32 v92, 0xbfb8aa3b, v86
	v_exp_f32_e32 v97, v92
	v_mad_i64_i32 v[98:99], s[0:1], v162, s92, v[132:133]
	v_rcp_f32_e32 v94, v95
	s_nop 0
	v_mul_f32_e32 v93, v93, v94
	v_lshl_add_u64 v[94:95], v[98:99], 0, v[122:123]
	v_cvt_pk_bf16_f32 v90, v100, v90
	v_cvt_pk_bf16_f32 v92, v101, v103
	v_cvt_pk_bf16_f32 v93, v96, v93
	global_store_dwordx4 v[94:95], v[90:93], off
	v_pk_mul_f32 v[82:83], v[82:83], v[160:161] op_sel_hi:[1,0]
	v_pk_mul_f32 v[88:89], v[88:89], v[160:161] op_sel_hi:[1,0]
	v_add_f32_e32 v90, 1.0, v97
	v_mul_f32_e32 v97, 0xbfb8aa3b, v82
	v_exp_f32_e32 v97, v97
	v_pk_mul_f32 v[84:85], v[84:85], v[160:161] op_sel_hi:[1,0]
	v_add_f32_e32 v93, 1.0, v97
	v_mul_f32_e32 v92, 0xbfb8aa3b, v87
	v_exp_f32_e32 v92, v92
	v_rcp_f32_e32 v91, v90
	s_nop 0
	v_mul_f32_e32 v86, v86, v91
	v_add_f32_e32 v92, 1.0, v92
	v_rcp_f32_e32 v90, v93
	s_nop 0
	v_mul_f32_e32 v90, v82, v90
	v_mul_f32_e32 v93, 0xbfb8aa3b, v83
	v_exp_f32_e32 v93, v93
	s_nop 0
	v_add_f32_e32 v93, 1.0, v93
	v_rcp_f32_e32 v82, v92
	s_nop 0
	v_mul_f32_e32 v82, v87, v82
	v_mul_f32_e32 v92, 0xbfb8aa3b, v88
	v_exp_f32_e32 v92, v92
	s_nop 0
	v_add_f32_e32 v92, 1.0, v92
	v_rcp_f32_e32 v87, v93
	s_nop 0
	v_mul_f32_e32 v87, v83, v87
	v_mul_f32_e32 v93, 0xbfb8aa3b, v84
	v_exp_f32_e32 v93, v93
	s_nop 0
	v_add_f32_e32 v93, 1.0, v93
	v_rcp_f32_e32 v83, v92
	s_nop 0
	v_mul_f32_e32 v83, v88, v83
	v_mul_f32_e32 v92, 0xbfb8aa3b, v89
	v_exp_f32_e32 v92, v92
	s_nop 0
	v_add_f32_e32 v92, 1.0, v92
	v_rcp_f32_e32 v88, v93
	s_nop 0
	v_mul_f32_e32 v88, v84, v88
	v_mul_f32_e32 v93, 0xbfb8aa3b, v85
	v_exp_f32_e32 v93, v93
	s_nop 0
	v_add_f32_e32 v93, 1.0, v93
	v_rcp_f32_e32 v84, v92
	s_nop 0
	v_mul_f32_e32 v84, v89, v84
	v_pk_mul_f32 v[78:79], v[78:79], v[156:157] op_sel_hi:[1,0]
	v_cvt_pk_bf16_f32 v82, v86, v82
	v_mul_f32_e32 v86, 0xbfb8aa3b, v78
	v_exp_f32_e32 v86, v86
	v_rcp_f32_e32 v89, v93
	s_nop 0
	v_mul_f32_e32 v85, v85, v89
	v_cvt_pk_bf16_f32 v83, v83, v84
	v_cvt_pk_bf16_f32 v84, v90, v87
	v_cvt_pk_bf16_f32 v85, v88, v85
	global_store_dwordx4 v[94:95], v[82:85], off offset:256
	v_pk_mul_f32 v[74:75], v[74:75], v[156:157] op_sel_hi:[1,0]
	v_pk_mul_f32 v[80:81], v[80:81], v[156:157] op_sel_hi:[1,0]
	v_add_f32_e32 v84, 1.0, v86
	v_mul_f32_e32 v89, 0xbfb8aa3b, v74
	v_exp_f32_e32 v89, v89
	v_pk_mul_f32 v[76:77], v[76:77], v[156:157] op_sel_hi:[1,0]
	v_add_f32_e32 v87, 1.0, v89
	v_mul_f32_e32 v86, 0xbfb8aa3b, v79
	v_exp_f32_e32 v86, v86
	v_rcp_f32_e32 v85, v84
	s_nop 0
	v_mul_f32_e32 v84, v78, v85
	v_add_f32_e32 v86, 1.0, v86
	v_rcp_f32_e32 v78, v87
	s_nop 0
	v_mul_f32_e32 v85, v74, v78
	v_mul_f32_e32 v87, 0xbfb8aa3b, v75
	v_exp_f32_e32 v87, v87
	s_nop 0
	v_add_f32_e32 v87, 1.0, v87
	v_rcp_f32_e32 v74, v86
	s_nop 0
	v_mul_f32_e32 v74, v79, v74
	v_mul_f32_e32 v86, 0xbfb8aa3b, v80
	v_exp_f32_e32 v86, v86
	s_nop 0
	v_add_f32_e32 v86, 1.0, v86
	v_mul_f32_e32 v79, 0xbfb8aa3b, v76
	v_rcp_f32_e32 v78, v87
	s_nop 0
	v_mul_f32_e32 v87, v75, v78
	v_exp_f32_e32 v79, v79
	s_nop 0
	v_add_f32_e32 v79, 1.0, v79
	v_rcp_f32_e32 v75, v86
	s_nop 0
	v_mul_f32_e32 v75, v80, v75
	v_mul_f32_e32 v86, 0xbfb8aa3b, v81
	v_exp_f32_e32 v86, v86
	s_nop 0
	v_add_f32_e32 v86, 1.0, v86
	v_rcp_f32_e32 v78, v79
	s_nop 0
	v_mul_f32_e32 v80, v76, v78
	v_mul_f32_e32 v79, 0xbfb8aa3b, v77
	v_exp_f32_e32 v79, v79
	s_nop 0
	v_add_f32_e32 v79, 1.0, v79
	v_rcp_f32_e32 v76, v86
	s_nop 0
	v_mul_f32_e32 v76, v81, v76
	v_pk_mul_f32 v[70:71], v[70:71], v[156:157] op_sel_hi:[1,0]
	v_cvt_pk_bf16_f32 v75, v75, v76
	v_mul_f32_e32 v76, 0xbfb8aa3b, v70
	v_exp_f32_e32 v81, v76
	v_mad_i64_i32 v[82:83], s[0:1], v158, s92, v[132:133]
	v_rcp_f32_e32 v78, v79
	s_nop 0
	v_mul_f32_e32 v77, v77, v78
	v_lshl_add_u64 v[78:79], v[82:83], 0, v[122:123]
	v_cvt_pk_bf16_f32 v74, v84, v74
	v_cvt_pk_bf16_f32 v76, v85, v87
	v_cvt_pk_bf16_f32 v77, v80, v77
	global_store_dwordx4 v[78:79], v[74:77], off
	v_pk_mul_f32 v[66:67], v[66:67], v[156:157] op_sel_hi:[1,0]
	v_pk_mul_f32 v[72:73], v[72:73], v[156:157] op_sel_hi:[1,0]
	v_add_f32_e32 v74, 1.0, v81
	v_mul_f32_e32 v81, 0xbfb8aa3b, v66
	v_exp_f32_e32 v81, v81
	v_pk_mul_f32 v[68:69], v[68:69], v[156:157] op_sel_hi:[1,0]
	v_add_f32_e32 v77, 1.0, v81
	v_mul_f32_e32 v76, 0xbfb8aa3b, v71
	v_exp_f32_e32 v76, v76
	v_rcp_f32_e32 v75, v74
	s_nop 0
	v_mul_f32_e32 v70, v70, v75
	v_add_f32_e32 v76, 1.0, v76
	v_rcp_f32_e32 v74, v77
	s_nop 0
	v_mul_f32_e32 v74, v66, v74
	v_mul_f32_e32 v77, 0xbfb8aa3b, v67
	v_exp_f32_e32 v77, v77
	s_nop 0
	v_add_f32_e32 v77, 1.0, v77
	v_rcp_f32_e32 v66, v76
	s_nop 0
	v_mul_f32_e32 v66, v71, v66
	v_mul_f32_e32 v76, 0xbfb8aa3b, v72
	v_exp_f32_e32 v76, v76
	s_nop 0
	v_add_f32_e32 v76, 1.0, v76
	v_rcp_f32_e32 v71, v77
	s_nop 0
	v_mul_f32_e32 v71, v67, v71
	v_mul_f32_e32 v77, 0xbfb8aa3b, v68
	v_exp_f32_e32 v77, v77
	s_nop 0
	v_add_f32_e32 v77, 1.0, v77
	v_rcp_f32_e32 v67, v76
	s_nop 0
	v_mul_f32_e32 v67, v72, v67
	v_mul_f32_e32 v76, 0xbfb8aa3b, v73
	v_exp_f32_e32 v76, v76
	s_nop 0
	v_add_f32_e32 v76, 1.0, v76
	v_rcp_f32_e32 v72, v77
	s_nop 0
	v_mul_f32_e32 v72, v68, v72
	v_mul_f32_e32 v77, 0xbfb8aa3b, v69
	v_exp_f32_e32 v77, v77
	s_nop 0
	v_add_f32_e32 v77, 1.0, v77
	v_rcp_f32_e32 v68, v76
	s_nop 0
	v_mul_f32_e32 v68, v73, v68
	v_pk_mul_f32 v[62:63], v[62:63], v[148:149] op_sel_hi:[1,0]
	v_cvt_pk_bf16_f32 v66, v70, v66
	v_mul_f32_e32 v70, 0xbfb8aa3b, v62
	v_exp_f32_e32 v70, v70
	v_rcp_f32_e32 v73, v77
	s_nop 0
	v_mul_f32_e32 v69, v69, v73
	v_cvt_pk_bf16_f32 v67, v67, v68
	v_cvt_pk_bf16_f32 v68, v74, v71
	v_cvt_pk_bf16_f32 v69, v72, v69
	global_store_dwordx4 v[78:79], v[66:69], off offset:256
	v_pk_mul_f32 v[58:59], v[58:59], v[148:149] op_sel_hi:[1,0]
	v_pk_mul_f32 v[64:65], v[64:65], v[148:149] op_sel_hi:[1,0]
	v_add_f32_e32 v68, 1.0, v70
	v_mul_f32_e32 v73, 0xbfb8aa3b, v58
	v_exp_f32_e32 v73, v73
	v_pk_mul_f32 v[60:61], v[60:61], v[148:149] op_sel_hi:[1,0]
	v_add_f32_e32 v71, 1.0, v73
	v_mul_f32_e32 v70, 0xbfb8aa3b, v63
	v_exp_f32_e32 v70, v70
	v_rcp_f32_e32 v69, v68
	s_nop 0
	v_mul_f32_e32 v68, v62, v69
	v_add_f32_e32 v70, 1.0, v70
	v_rcp_f32_e32 v62, v71
	s_nop 0
	v_mul_f32_e32 v69, v58, v62
	v_mul_f32_e32 v71, 0xbfb8aa3b, v59
	v_exp_f32_e32 v71, v71
	s_nop 0
	v_add_f32_e32 v71, 1.0, v71
	v_rcp_f32_e32 v58, v70
	s_nop 0
	v_mul_f32_e32 v58, v63, v58
	v_mul_f32_e32 v70, 0xbfb8aa3b, v64
	v_exp_f32_e32 v70, v70
	s_nop 0
	v_add_f32_e32 v70, 1.0, v70
	v_mul_f32_e32 v63, 0xbfb8aa3b, v60
	v_rcp_f32_e32 v62, v71
	s_nop 0
	v_mul_f32_e32 v71, v59, v62
	v_exp_f32_e32 v63, v63
	s_nop 0
	v_add_f32_e32 v63, 1.0, v63
	v_rcp_f32_e32 v59, v70
	s_nop 0
	v_mul_f32_e32 v59, v64, v59
	v_mul_f32_e32 v70, 0xbfb8aa3b, v65
	v_exp_f32_e32 v70, v70
	s_nop 0
	v_add_f32_e32 v70, 1.0, v70
	v_rcp_f32_e32 v62, v63
	s_nop 0
	v_mul_f32_e32 v64, v60, v62
	v_mul_f32_e32 v63, 0xbfb8aa3b, v61
	v_exp_f32_e32 v63, v63
	s_nop 0
	v_add_f32_e32 v63, 1.0, v63
	v_rcp_f32_e32 v60, v70
	s_nop 0
	v_mul_f32_e32 v60, v65, v60
	v_pk_mul_f32 v[54:55], v[54:55], v[148:149] op_sel_hi:[1,0]
	v_cvt_pk_bf16_f32 v59, v59, v60
	v_mul_f32_e32 v60, 0xbfb8aa3b, v54
	v_exp_f32_e32 v65, v60
	v_mad_i64_i32 v[66:67], s[0:1], v157, s92, v[132:133]
	v_rcp_f32_e32 v62, v63
	s_nop 0
	v_mul_f32_e32 v61, v61, v62
	v_lshl_add_u64 v[62:63], v[66:67], 0, v[122:123]
	v_cvt_pk_bf16_f32 v58, v68, v58
	v_cvt_pk_bf16_f32 v60, v69, v71
	v_cvt_pk_bf16_f32 v61, v64, v61
	global_store_dwordx4 v[62:63], v[58:61], off
	v_pk_mul_f32 v[50:51], v[50:51], v[148:149] op_sel_hi:[1,0]
	v_pk_mul_f32 v[56:57], v[56:57], v[148:149] op_sel_hi:[1,0]
	v_add_f32_e32 v58, 1.0, v65
	v_mul_f32_e32 v65, 0xbfb8aa3b, v50
	v_exp_f32_e32 v65, v65
	v_pk_mul_f32 v[52:53], v[52:53], v[148:149] op_sel_hi:[1,0]
	v_add_f32_e32 v61, 1.0, v65
	v_mul_f32_e32 v60, 0xbfb8aa3b, v55
	v_exp_f32_e32 v60, v60
	v_rcp_f32_e32 v59, v58
	s_nop 0
	v_mul_f32_e32 v54, v54, v59
	v_add_f32_e32 v60, 1.0, v60
	v_rcp_f32_e32 v58, v61
	s_nop 0
	v_mul_f32_e32 v58, v50, v58
	v_mul_f32_e32 v61, 0xbfb8aa3b, v51
	v_exp_f32_e32 v61, v61
	s_nop 0
	v_add_f32_e32 v61, 1.0, v61
	v_rcp_f32_e32 v50, v60
	s_nop 0
	v_mul_f32_e32 v50, v55, v50
	v_mul_f32_e32 v60, 0xbfb8aa3b, v56
	v_exp_f32_e32 v60, v60
	s_nop 0
	v_add_f32_e32 v60, 1.0, v60
	v_rcp_f32_e32 v55, v61
	s_nop 0
	v_mul_f32_e32 v55, v51, v55
	v_mul_f32_e32 v61, 0xbfb8aa3b, v52
	v_exp_f32_e32 v61, v61
	s_nop 0
	v_add_f32_e32 v61, 1.0, v61
	v_rcp_f32_e32 v51, v60
	s_nop 0
	v_mul_f32_e32 v51, v56, v51
	v_mul_f32_e32 v60, 0xbfb8aa3b, v57
	v_exp_f32_e32 v60, v60
	s_nop 0
	v_add_f32_e32 v60, 1.0, v60
	v_rcp_f32_e32 v56, v61
	s_nop 0
	v_mul_f32_e32 v56, v52, v56
	v_mul_f32_e32 v61, 0xbfb8aa3b, v53
	v_exp_f32_e32 v61, v61
	s_nop 0
	v_add_f32_e32 v61, 1.0, v61
	v_rcp_f32_e32 v52, v60
	s_nop 0
	v_mul_f32_e32 v52, v57, v52
	v_pk_mul_f32 v[46:47], v[46:47], v[136:137] op_sel_hi:[1,0]
	v_cvt_pk_bf16_f32 v50, v54, v50
	v_mul_f32_e32 v54, 0xbfb8aa3b, v46
	v_exp_f32_e32 v54, v54
	v_rcp_f32_e32 v57, v61
	s_nop 0
	v_mul_f32_e32 v53, v53, v57
	v_cvt_pk_bf16_f32 v51, v51, v52
	v_cvt_pk_bf16_f32 v52, v58, v55
	v_cvt_pk_bf16_f32 v53, v56, v53
	global_store_dwordx4 v[62:63], v[50:53], off offset:256
	v_pk_mul_f32 v[42:43], v[42:43], v[136:137] op_sel_hi:[1,0]
	v_pk_mul_f32 v[48:49], v[48:49], v[136:137] op_sel_hi:[1,0]
	v_add_f32_e32 v52, 1.0, v54
	v_mul_f32_e32 v57, 0xbfb8aa3b, v42
	v_exp_f32_e32 v57, v57
	v_pk_mul_f32 v[44:45], v[44:45], v[136:137] op_sel_hi:[1,0]
	v_add_f32_e32 v55, 1.0, v57
	v_mul_f32_e32 v54, 0xbfb8aa3b, v47
	v_exp_f32_e32 v54, v54
	v_rcp_f32_e32 v53, v52
	s_nop 0
	v_mul_f32_e32 v52, v46, v53
	v_add_f32_e32 v54, 1.0, v54
	v_rcp_f32_e32 v46, v55
	s_nop 0
	v_mul_f32_e32 v53, v42, v46
	v_mul_f32_e32 v55, 0xbfb8aa3b, v43
	v_exp_f32_e32 v55, v55
	s_nop 0
	v_add_f32_e32 v55, 1.0, v55
	v_rcp_f32_e32 v42, v54
	s_nop 0
	v_mul_f32_e32 v42, v47, v42
	v_mul_f32_e32 v54, 0xbfb8aa3b, v48
	v_exp_f32_e32 v54, v54
	s_nop 0
	v_add_f32_e32 v54, 1.0, v54
	v_mul_f32_e32 v47, 0xbfb8aa3b, v44
	v_rcp_f32_e32 v46, v55
	s_nop 0
	v_mul_f32_e32 v55, v43, v46
	v_exp_f32_e32 v47, v47
	s_nop 0
	v_add_f32_e32 v47, 1.0, v47
	v_rcp_f32_e32 v43, v54
	s_nop 0
	v_mul_f32_e32 v43, v48, v43
	v_mul_f32_e32 v54, 0xbfb8aa3b, v49
	v_exp_f32_e32 v54, v54
	s_nop 0
	v_add_f32_e32 v54, 1.0, v54
	v_rcp_f32_e32 v46, v47
	s_nop 0
	v_mul_f32_e32 v48, v44, v46
	v_mul_f32_e32 v47, 0xbfb8aa3b, v45
	v_exp_f32_e32 v47, v47
	s_nop 0
	v_add_f32_e32 v47, 1.0, v47
	v_rcp_f32_e32 v44, v54
	s_nop 0
	v_mul_f32_e32 v44, v49, v44
	v_pk_mul_f32 v[38:39], v[38:39], v[136:137] op_sel_hi:[1,0]
	v_cvt_pk_bf16_f32 v43, v43, v44
	v_mul_f32_e32 v44, 0xbfb8aa3b, v38
	v_exp_f32_e32 v49, v44
	v_mad_i64_i32 v[50:51], s[0:1], v137, s92, v[132:133]
	v_rcp_f32_e32 v46, v47
	s_nop 0
	v_mul_f32_e32 v45, v45, v46
	v_lshl_add_u64 v[46:47], v[50:51], 0, v[122:123]
	v_cvt_pk_bf16_f32 v42, v52, v42
	v_cvt_pk_bf16_f32 v44, v53, v55
	v_cvt_pk_bf16_f32 v45, v48, v45
	global_store_dwordx4 v[46:47], v[42:45], off
	v_pk_mul_f32 v[34:35], v[34:35], v[136:137] op_sel_hi:[1,0]
	v_pk_mul_f32 v[40:41], v[40:41], v[136:137] op_sel_hi:[1,0]
	v_add_f32_e32 v42, 1.0, v49
	v_mul_f32_e32 v49, 0xbfb8aa3b, v34
	v_exp_f32_e32 v49, v49
	v_pk_mul_f32 v[36:37], v[36:37], v[136:137] op_sel_hi:[1,0]
	v_add_f32_e32 v45, 1.0, v49
	v_mul_f32_e32 v44, 0xbfb8aa3b, v39
	v_exp_f32_e32 v44, v44
	v_rcp_f32_e32 v43, v42
	s_nop 0
	v_mul_f32_e32 v38, v38, v43
	v_add_f32_e32 v44, 1.0, v44
	v_rcp_f32_e32 v42, v45
	s_nop 0
	v_mul_f32_e32 v42, v34, v42
	v_mul_f32_e32 v45, 0xbfb8aa3b, v35
	v_exp_f32_e32 v45, v45
	s_nop 0
	v_add_f32_e32 v45, 1.0, v45
	v_rcp_f32_e32 v34, v44
	s_nop 0
	v_mul_f32_e32 v34, v39, v34
	v_mul_f32_e32 v44, 0xbfb8aa3b, v40
	v_exp_f32_e32 v44, v44
	s_nop 0
	v_add_f32_e32 v44, 1.0, v44
	v_rcp_f32_e32 v39, v45
	s_nop 0
	v_mul_f32_e32 v39, v35, v39
	v_mul_f32_e32 v45, 0xbfb8aa3b, v36
	v_exp_f32_e32 v45, v45
	s_nop 0
	v_add_f32_e32 v45, 1.0, v45
	v_rcp_f32_e32 v35, v44
	s_nop 0
	v_mul_f32_e32 v35, v40, v35
	v_mul_f32_e32 v44, 0xbfb8aa3b, v41
	v_exp_f32_e32 v44, v44
	s_nop 0
	v_add_f32_e32 v44, 1.0, v44
	v_rcp_f32_e32 v40, v45
	s_nop 0
	v_mul_f32_e32 v40, v36, v40
	v_mul_f32_e32 v45, 0xbfb8aa3b, v37
	v_exp_f32_e32 v45, v45
	s_nop 0
	v_add_f32_e32 v45, 1.0, v45
	v_rcp_f32_e32 v36, v44
	s_nop 0
	v_mul_f32_e32 v36, v41, v36
	v_pk_mul_f32 v[30:31], v[30:31], v[134:135] op_sel_hi:[1,0]
	v_cvt_pk_bf16_f32 v34, v38, v34
	v_mul_f32_e32 v38, 0xbfb8aa3b, v30
	v_exp_f32_e32 v38, v38
	v_rcp_f32_e32 v41, v45
	s_nop 0
	v_mul_f32_e32 v37, v37, v41
	v_cvt_pk_bf16_f32 v35, v35, v36
	v_cvt_pk_bf16_f32 v36, v42, v39
	v_cvt_pk_bf16_f32 v37, v40, v37
	global_store_dwordx4 v[46:47], v[34:37], off offset:256
	v_pk_mul_f32 v[26:27], v[26:27], v[134:135] op_sel_hi:[1,0]
	v_pk_mul_f32 v[32:33], v[32:33], v[134:135] op_sel_hi:[1,0]
	v_add_f32_e32 v36, 1.0, v38
	v_mul_f32_e32 v41, 0xbfb8aa3b, v26
	v_exp_f32_e32 v41, v41
	v_pk_mul_f32 v[28:29], v[28:29], v[134:135] op_sel_hi:[1,0]
	v_add_f32_e32 v39, 1.0, v41
	v_mul_f32_e32 v38, 0xbfb8aa3b, v31
	v_exp_f32_e32 v38, v38
	v_rcp_f32_e32 v37, v36
	s_nop 0
	v_mul_f32_e32 v36, v30, v37
	v_add_f32_e32 v38, 1.0, v38
	v_rcp_f32_e32 v30, v39
	s_nop 0
	v_mul_f32_e32 v37, v26, v30
	v_mul_f32_e32 v39, 0xbfb8aa3b, v27
	v_exp_f32_e32 v39, v39
	s_nop 0
	v_add_f32_e32 v39, 1.0, v39
	v_rcp_f32_e32 v26, v38
	s_nop 0
	v_mul_f32_e32 v26, v31, v26
	v_mul_f32_e32 v38, 0xbfb8aa3b, v32
	v_exp_f32_e32 v38, v38
	s_nop 0
	v_add_f32_e32 v38, 1.0, v38
	v_mul_f32_e32 v31, 0xbfb8aa3b, v28
	v_rcp_f32_e32 v30, v39
	s_nop 0
	v_mul_f32_e32 v39, v27, v30
	v_exp_f32_e32 v31, v31
	s_nop 0
	v_add_f32_e32 v31, 1.0, v31
	v_rcp_f32_e32 v27, v38
	s_nop 0
	v_mul_f32_e32 v27, v32, v27
	v_mul_f32_e32 v38, 0xbfb8aa3b, v33
	v_exp_f32_e32 v38, v38
	s_nop 0
	v_add_f32_e32 v38, 1.0, v38
	v_rcp_f32_e32 v30, v31
	s_nop 0
	v_mul_f32_e32 v32, v28, v30
	v_mul_f32_e32 v31, 0xbfb8aa3b, v29
	v_exp_f32_e32 v31, v31
	s_nop 0
	v_add_f32_e32 v31, 1.0, v31
	v_rcp_f32_e32 v28, v38
	s_nop 0
	v_mul_f32_e32 v28, v33, v28
	v_pk_mul_f32 v[22:23], v[22:23], v[134:135] op_sel_hi:[1,0]
	v_cvt_pk_bf16_f32 v27, v27, v28
	v_mul_f32_e32 v28, 0xbfb8aa3b, v22
	v_exp_f32_e32 v33, v28
	v_mad_i64_i32 v[34:35], s[0:1], v135, s92, v[132:133]
	v_rcp_f32_e32 v30, v31
	s_nop 0
	v_mul_f32_e32 v29, v29, v30
	v_lshl_add_u64 v[30:31], v[34:35], 0, v[122:123]
	v_cvt_pk_bf16_f32 v26, v36, v26
	v_cvt_pk_bf16_f32 v28, v37, v39
	v_cvt_pk_bf16_f32 v29, v32, v29
	global_store_dwordx4 v[30:31], v[26:29], off
	v_pk_mul_f32 v[18:19], v[18:19], v[134:135] op_sel_hi:[1,0]
	v_pk_mul_f32 v[24:25], v[24:25], v[134:135] op_sel_hi:[1,0]
	v_add_f32_e32 v26, 1.0, v33
	v_mul_f32_e32 v33, 0xbfb8aa3b, v18
	v_exp_f32_e32 v33, v33
	v_pk_mul_f32 v[20:21], v[20:21], v[134:135] op_sel_hi:[1,0]
	v_add_f32_e32 v29, 1.0, v33
	v_mul_f32_e32 v28, 0xbfb8aa3b, v23
	v_exp_f32_e32 v28, v28
	v_rcp_f32_e32 v27, v26
	s_nop 0
	v_mul_f32_e32 v22, v22, v27
	v_add_f32_e32 v28, 1.0, v28
	v_rcp_f32_e32 v26, v29
	s_nop 0
	v_mul_f32_e32 v26, v18, v26
	v_mul_f32_e32 v29, 0xbfb8aa3b, v19
	v_exp_f32_e32 v29, v29
	s_nop 0
	v_add_f32_e32 v29, 1.0, v29
	v_rcp_f32_e32 v18, v28
	s_nop 0
	v_mul_f32_e32 v18, v23, v18
	v_mul_f32_e32 v28, 0xbfb8aa3b, v24
	v_exp_f32_e32 v28, v28
	s_nop 0
	v_add_f32_e32 v28, 1.0, v28
	v_rcp_f32_e32 v23, v29
	s_nop 0
	v_mul_f32_e32 v23, v19, v23
	v_mul_f32_e32 v29, 0xbfb8aa3b, v20
	v_exp_f32_e32 v29, v29
	s_nop 0
	v_add_f32_e32 v29, 1.0, v29
	v_rcp_f32_e32 v19, v28
	s_nop 0
	v_mul_f32_e32 v19, v24, v19
	v_mul_f32_e32 v28, 0xbfb8aa3b, v25
	v_exp_f32_e32 v28, v28
	s_nop 0
	v_add_f32_e32 v28, 1.0, v28
	v_rcp_f32_e32 v24, v29
	s_nop 0
	v_mul_f32_e32 v24, v20, v24
	v_mul_f32_e32 v29, 0xbfb8aa3b, v21
	v_exp_f32_e32 v29, v29
	s_nop 0
	v_add_f32_e32 v29, 1.0, v29
	v_rcp_f32_e32 v20, v28
	s_nop 0
	v_mul_f32_e32 v20, v25, v20
	v_pk_mul_f32 v[14:15], v[14:15], v[130:131] op_sel_hi:[1,0]
	v_cvt_pk_bf16_f32 v18, v22, v18
	v_mul_f32_e32 v22, 0xbfb8aa3b, v14
	v_exp_f32_e32 v22, v22
	v_rcp_f32_e32 v25, v29
	s_nop 0
	v_mul_f32_e32 v21, v21, v25
	v_cvt_pk_bf16_f32 v19, v19, v20
	v_cvt_pk_bf16_f32 v20, v26, v23
	v_cvt_pk_bf16_f32 v21, v24, v21
	global_store_dwordx4 v[30:31], v[18:21], off offset:256
	v_pk_mul_f32 v[10:11], v[10:11], v[130:131] op_sel_hi:[1,0]
	v_pk_mul_f32 v[16:17], v[16:17], v[130:131] op_sel_hi:[1,0]
	v_add_f32_e32 v20, 1.0, v22
	v_mul_f32_e32 v25, 0xbfb8aa3b, v10
	v_exp_f32_e32 v25, v25
	v_pk_mul_f32 v[12:13], v[12:13], v[130:131] op_sel_hi:[1,0]
	v_add_f32_e32 v23, 1.0, v25
	v_mul_f32_e32 v22, 0xbfb8aa3b, v15
	v_exp_f32_e32 v22, v22
	v_rcp_f32_e32 v21, v20
	s_nop 0
	v_mul_f32_e32 v20, v14, v21
	v_add_f32_e32 v22, 1.0, v22
	v_rcp_f32_e32 v14, v23
	s_nop 0
	v_mul_f32_e32 v21, v10, v14
	v_mul_f32_e32 v23, 0xbfb8aa3b, v11
	v_exp_f32_e32 v23, v23
	s_nop 0
	v_add_f32_e32 v23, 1.0, v23
	v_rcp_f32_e32 v10, v22
	s_nop 0
	v_mul_f32_e32 v10, v15, v10
	v_mul_f32_e32 v22, 0xbfb8aa3b, v16
	v_exp_f32_e32 v22, v22
	s_nop 0
	v_add_f32_e32 v22, 1.0, v22
	v_mul_f32_e32 v15, 0xbfb8aa3b, v12
	v_rcp_f32_e32 v14, v23
	s_nop 0
	v_mul_f32_e32 v23, v11, v14
	v_exp_f32_e32 v15, v15
	s_nop 0
	v_add_f32_e32 v15, 1.0, v15
	v_rcp_f32_e32 v11, v22
	s_nop 0
	v_mul_f32_e32 v11, v16, v11
	v_mul_f32_e32 v22, 0xbfb8aa3b, v17
	v_exp_f32_e32 v22, v22
	s_nop 0
	v_add_f32_e32 v22, 1.0, v22
	v_rcp_f32_e32 v14, v15
	s_nop 0
	v_mul_f32_e32 v16, v12, v14
	v_mul_f32_e32 v15, 0xbfb8aa3b, v13
	v_exp_f32_e32 v15, v15
	s_nop 0
	v_add_f32_e32 v15, 1.0, v15
	v_rcp_f32_e32 v12, v22
	s_nop 0
	v_mul_f32_e32 v12, v17, v12
	v_pk_mul_f32 v[6:7], v[6:7], v[130:131] op_sel_hi:[1,0]
	v_cvt_pk_bf16_f32 v11, v11, v12
	v_mul_f32_e32 v12, 0xbfb8aa3b, v6
	v_exp_f32_e32 v17, v12
	v_mad_i64_i32 v[18:19], s[0:1], v131, s92, v[132:133]
	v_rcp_f32_e32 v14, v15
	s_nop 0
	v_mul_f32_e32 v13, v13, v14
	v_lshl_add_u64 v[14:15], v[18:19], 0, v[122:123]
	v_cvt_pk_bf16_f32 v10, v20, v10
	v_cvt_pk_bf16_f32 v12, v21, v23
	v_cvt_pk_bf16_f32 v13, v16, v13
	global_store_dwordx4 v[14:15], v[10:13], off
	v_pk_mul_f32 v[2:3], v[2:3], v[130:131] op_sel_hi:[1,0]
	v_pk_mul_f32 v[8:9], v[8:9], v[130:131] op_sel_hi:[1,0]
	v_add_f32_e32 v10, 1.0, v17
	v_mul_f32_e32 v17, 0xbfb8aa3b, v2
	v_exp_f32_e32 v17, v17
	v_pk_mul_f32 v[4:5], v[4:5], v[130:131] op_sel_hi:[1,0]
	v_add_f32_e32 v13, 1.0, v17
	v_mul_f32_e32 v12, 0xbfb8aa3b, v7
	v_exp_f32_e32 v12, v12
	v_rcp_f32_e32 v11, v10
	s_nop 0
	v_mul_f32_e32 v6, v6, v11
	v_add_f32_e32 v12, 1.0, v12
	v_rcp_f32_e32 v10, v13
	s_nop 0
	v_mul_f32_e32 v10, v2, v10
	v_mul_f32_e32 v13, 0xbfb8aa3b, v3
	v_exp_f32_e32 v13, v13
	s_nop 0
	v_add_f32_e32 v13, 1.0, v13
	v_rcp_f32_e32 v2, v12
	s_nop 0
	v_mul_f32_e32 v2, v7, v2
	v_mul_f32_e32 v12, 0xbfb8aa3b, v8
	v_exp_f32_e32 v12, v12
	s_nop 0
	v_add_f32_e32 v12, 1.0, v12
	v_rcp_f32_e32 v7, v13
	s_nop 0
	v_mul_f32_e32 v7, v3, v7
	v_mul_f32_e32 v13, 0xbfb8aa3b, v4
	v_exp_f32_e32 v13, v13
	s_nop 0
	v_add_f32_e32 v13, 1.0, v13
	v_rcp_f32_e32 v3, v12
	s_nop 0
	v_mul_f32_e32 v3, v8, v3
	v_mul_f32_e32 v12, 0xbfb8aa3b, v9
	v_exp_f32_e32 v12, v12
	s_nop 0
	v_add_f32_e32 v12, 1.0, v12
	v_rcp_f32_e32 v8, v13
	s_nop 0
	v_mul_f32_e32 v8, v4, v8
	v_mul_f32_e32 v13, 0xbfb8aa3b, v5
	v_exp_f32_e32 v13, v13
	s_nop 0
	v_add_f32_e32 v13, 1.0, v13
	v_rcp_f32_e32 v4, v12
	s_nop 0
	v_mul_f32_e32 v4, v9, v4
	v_cvt_pk_bf16_f32 v2, v6, v2
	v_rcp_f32_e32 v9, v13
	s_nop 0
	v_mul_f32_e32 v5, v5, v9
	v_cvt_pk_bf16_f32 v3, v3, v4
	v_cvt_pk_bf16_f32 v4, v10, v7
	v_cvt_pk_bf16_f32 v5, v8, v5
	global_store_dwordx4 v[14:15], v[2:5], off offset:256
	s_andn2_b64 vcc, exec, s[4:5]
	s_mov_b64 s[4:5], -1
	s_cbranch_vccnz .LBB0_432

.LBB0_1006:
	s_lshl_b32 s1, s94, 8
	s_lshl_b32 s0, s62, 8
	s_and_b32 s1, s1, 0x300
	v_or_b32_e32 v132, s1, v175
	v_add_u32_e32 v160, s0, v1
	s_cmp_gt_u32 s94, 7
	v_lshlrev_b32_e32 v130, 1, v132
	v_ashrrev_i32_e32 v161, 31, v160
	v_or_b32_e32 v164, 16, v160
	v_or_b32_e32 v166, 32, v160
	v_or_b32_e32 v162, 48, v160
	s_cbranch_scc0 .LBB0_1008
	v_mov_b32_e32 v131, v155
	v_lshl_add_u64 v[138:139], s[26:27], 0, v[130:131]
	v_lshlrev_b64 v[134:135], 11, v[160:161]
	v_lshl_add_u64 v[140:141], v[138:139], 0, v[134:135]
	v_cvt_pk_bf16_f32 v134, v126, v127
	v_cvt_pk_bf16_f32 v135, v128, v129
	v_ashrrev_i32_e32 v165, 31, v164
	v_cvt_pk_bf16_f32 v136, v122, v123
	v_cvt_pk_bf16_f32 v137, v124, v125
	global_store_dwordx4 v[140:141], v[134:137], off
	v_ashrrev_i32_e32 v167, 31, v166
	v_add_co_u32_e32 v170, vcc, s90, v140
	v_lshlrev_b64 v[134:135], 11, v[164:165]
	v_lshl_add_u64 v[142:143], v[138:139], 0, v[134:135]
	v_cvt_pk_bf16_f32 v134, v118, v119
	v_cvt_pk_bf16_f32 v135, v120, v121
	v_cvt_pk_bf16_f32 v136, v114, v115
	v_cvt_pk_bf16_f32 v137, v116, v117
	global_store_dwordx4 v[142:143], v[134:137], off
	v_ashrrev_i32_e32 v163, 31, v162
	v_addc_co_u32_e32 v171, vcc, 0, v141, vcc
	v_lshlrev_b64 v[134:135], 11, v[166:167]
	v_lshl_add_u64 v[144:145], v[138:139], 0, v[134:135]
	v_cvt_pk_bf16_f32 v134, v110, v111
	v_cvt_pk_bf16_f32 v135, v112, v113
	v_cvt_pk_bf16_f32 v136, v106, v107
	v_cvt_pk_bf16_f32 v137, v108, v109
	global_store_dwordx4 v[144:145], v[134:137], off
	v_add_co_u32_e32 v172, vcc, s91, v140
	s_nop 0
	v_lshlrev_b64 v[134:135], 11, v[162:163]
	v_lshl_add_u64 v[138:139], v[138:139], 0, v[134:135]
	v_cvt_pk_bf16_f32 v134, v102, v103
	v_cvt_pk_bf16_f32 v135, v104, v105
	v_cvt_pk_bf16_f32 v136, v98, v99
	v_cvt_pk_bf16_f32 v137, v100, v101
	v_addc_co_u32_e32 v173, vcc, 0, v141, vcc
	s_nop 0
	global_store_dwordx4 v[138:139], v[134:137], off
	v_add_co_u32_e32 v182, vcc, s92, v140
	s_nop 0
	v_cvt_pk_bf16_f32 v134, v94, v95
	v_cvt_pk_bf16_f32 v135, v96, v97
	v_cvt_pk_bf16_f32 v136, v90, v91
	v_cvt_pk_bf16_f32 v137, v92, v93
	global_store_dwordx4 v[170:171], v[134:137], off
	v_addc_co_u32_e32 v183, vcc, 0, v141, vcc
	s_nop 0
	v_cvt_pk_bf16_f32 v134, v86, v87
	v_cvt_pk_bf16_f32 v135, v88, v89
	v_cvt_pk_bf16_f32 v136, v82, v83
	v_cvt_pk_bf16_f32 v137, v84, v85
	global_store_dwordx4 v[172:173], v[134:137], off
	v_add_co_u32_e32 v184, vcc, s93, v140
	s_nop 0
	v_cvt_pk_bf16_f32 v134, v78, v79
	v_cvt_pk_bf16_f32 v135, v80, v81
	v_cvt_pk_bf16_f32 v136, v74, v75
	v_cvt_pk_bf16_f32 v137, v76, v77
	global_store_dwordx4 v[182:183], v[134:137], off
	v_addc_co_u32_e32 v185, vcc, 0, v141, vcc
	s_nop 0
	v_cvt_pk_bf16_f32 v134, v70, v71
	v_cvt_pk_bf16_f32 v135, v72, v73
	v_cvt_pk_bf16_f32 v136, v66, v67
	v_cvt_pk_bf16_f32 v137, v68, v69
	global_store_dwordx4 v[184:185], v[134:137], off
	v_lshl_add_u64 v[168:169], v[140:141], 0, s[34:35]
	v_lshl_add_u64 v[170:171], v[140:141], 0, s[36:37]
	v_cvt_pk_bf16_f32 v134, v62, v63
	v_cvt_pk_bf16_f32 v135, v64, v65
	v_cvt_pk_bf16_f32 v136, v58, v59
	v_cvt_pk_bf16_f32 v137, v60, v61
	global_store_dwordx4 v[140:141], v[134:137], off offset:256
	v_lshl_add_u64 v[172:173], v[140:141], 0, s[38:39]
	v_lshl_add_u64 v[182:183], v[140:141], 0, s[40:41]
	v_cvt_pk_bf16_f32 v134, v54, v55
	v_cvt_pk_bf16_f32 v135, v56, v57
	v_cvt_pk_bf16_f32 v136, v50, v51
	v_cvt_pk_bf16_f32 v137, v52, v53
	global_store_dwordx4 v[142:143], v[134:137], off offset:256
	s_mov_b64 s[6:7], 0
	s_nop 0
	v_cvt_pk_bf16_f32 v134, v46, v47
	v_cvt_pk_bf16_f32 v135, v48, v49
	v_cvt_pk_bf16_f32 v136, v42, v43
	v_cvt_pk_bf16_f32 v137, v44, v45
	global_store_dwordx4 v[144:145], v[134:137], off offset:256
	s_nop 1
	v_cvt_pk_bf16_f32 v134, v38, v39
	v_cvt_pk_bf16_f32 v135, v40, v41
	v_cvt_pk_bf16_f32 v136, v34, v35
	v_cvt_pk_bf16_f32 v137, v36, v37
	global_store_dwordx4 v[138:139], v[134:137], off offset:256
	s_nop 1
	v_cvt_pk_bf16_f32 v134, v30, v31
	v_cvt_pk_bf16_f32 v135, v32, v33
	v_cvt_pk_bf16_f32 v136, v26, v27
	v_cvt_pk_bf16_f32 v137, v28, v29
	global_store_dwordx4 v[168:169], v[134:137], off offset:256
	s_nop 1
	v_cvt_pk_bf16_f32 v134, v22, v23
	v_cvt_pk_bf16_f32 v135, v24, v25
	v_cvt_pk_bf16_f32 v136, v18, v19
	v_cvt_pk_bf16_f32 v137, v20, v21
	global_store_dwordx4 v[170:171], v[134:137], off offset:256
	s_nop 1
	v_cvt_pk_bf16_f32 v134, v14, v15
	v_cvt_pk_bf16_f32 v135, v16, v17
	v_cvt_pk_bf16_f32 v136, v10, v11
	v_cvt_pk_bf16_f32 v137, v12, v13
	global_store_dwordx4 v[172:173], v[134:137], off offset:256
	s_nop 1
	v_cvt_pk_bf16_f32 v134, v6, v7
	v_cvt_pk_bf16_f32 v135, v8, v9
	v_cvt_pk_bf16_f32 v136, v2, v3
	v_cvt_pk_bf16_f32 v137, v4, v5
	global_store_dwordx4 v[182:183], v[134:137], off offset:256
.LBB0_1008:
	s_andn2_b64 vcc, exec, s[6:7]
	s_cbranch_vccnz .LBB0_1010
	v_lshlrev_b32_e32 v154, 2, v132
	v_lshl_add_u64 v[132:133], s[18:19], 0, v[154:155]
	flat_load_dwordx4 v[142:145], v[132:133]
	flat_load_dwordx4 v[138:141], v[132:133] offset:16
	v_mov_b32_e32 v131, v155
	v_lshl_add_u64 v[170:171], s[28:29], 0, v[130:131]
	v_lshlrev_b64 v[160:161], 11, v[160:161]
	v_lshl_add_u64 v[160:161], v[170:171], 0, v[160:161]
	flat_load_dwordx4 v[134:137], v[132:133] offset:512
	s_nop 0
	flat_load_dwordx4 v[130:133], v[132:133] offset:528
	s_waitcnt vmcnt(0) lgkmcnt(0)
	v_add_f32_e32 v154, v126, v142
	v_add_f32_e32 v163, v122, v138
	v_mul_f32_e32 v154, 0xbfb8aa3b, v154
	v_add_f32_e32 v165, v127, v143
	v_mul_f32_e32 v163, 0xbfb8aa3b, v163
	v_exp_f32_e32 v154, v154
	v_mul_f32_e32 v165, 0xbfb8aa3b, v165
	v_exp_f32_e32 v163, v163
	v_add_f32_e32 v167, v123, v139
	v_exp_f32_e32 v165, v165
	v_add_f32_e32 v168, v128, v144
	v_mul_f32_e32 v167, 0xbfb8aa3b, v167
	v_mul_f32_e32 v168, 0xbfb8aa3b, v168
	v_exp_f32_e32 v167, v167
	v_add_f32_e32 v154, 1.0, v154
	v_exp_f32_e32 v168, v168
	v_add_f32_e32 v163, 1.0, v163
	v_add_f32_e32 v165, 1.0, v165
	v_add_f32_e32 v167, 1.0, v167
	v_add_f32_e32 v169, v124, v140
	v_add_f32_e32 v168, 1.0, v168
	v_mul_f32_e32 v169, 0xbfb8aa3b, v169
	v_exp_f32_e32 v169, v169
	s_nop 0
	v_add_f32_e32 v169, 1.0, v169
	v_rcp_f32_e32 v154, v154
	v_rcp_f32_e32 v163, v163
	v_add_f32_e32 v181, v129, v145
	v_mul_f32_e32 v181, 0xbfb8aa3b, v181
	v_rcp_f32_e32 v165, v165
	v_exp_f32_e32 v181, v181
	v_rcp_f32_e32 v167, v167
	v_rcp_f32_e32 v168, v168
	v_add_f32_e32 v181, 1.0, v181
	v_add_f32_e32 v184, v125, v141
	v_rcp_f32_e32 v169, v169
	v_mul_f32_e32 v184, 0xbfb8aa3b, v184
	v_exp_f32_e32 v184, v184
	s_nop 0
	v_add_f32_e32 v182, 1.0, v184
	v_rcp_f32_e32 v172, v181
	v_add_f32_e32 v181, v118, v142
	v_mul_f32_e32 v181, 0xbfb8aa3b, v181
	v_exp_f32_e32 v181, v181
	v_rcp_f32_e32 v173, v182
	v_cvt_pk_bf16_f32 v182, v154, v165
	v_cvt_pk_bf16_f32 v183, v168, v172
	v_add_f32_e32 v154, 1.0, v181
	v_cvt_pk_bf16_f32 v185, v169, v173
	v_add_f32_e32 v169, v114, v138
	v_cvt_pk_bf16_f32 v184, v163, v167
	v_mul_f32_e32 v169, 0xbfb8aa3b, v169
	v_exp_f32_e32 v169, v169
	s_nop 0
	v_add_f32_e32 v165, 1.0, v169
	v_add_f32_e32 v168, v119, v143
	v_mul_f32_e32 v168, 0xbfb8aa3b, v168
	v_rcp_f32_e32 v154, v154
	v_exp_f32_e32 v168, v168
	s_nop 0
	v_add_f32_e32 v168, 1.0, v168
	v_add_f32_e32 v172, v115, v139
	v_rcp_f32_e32 v163, v165
	v_mul_f32_e32 v172, 0xbfb8aa3b, v172
	v_exp_f32_e32 v172, v172
	s_nop 0
	v_add_f32_e32 v169, 1.0, v172
	v_add_f32_e32 v173, v120, v144
	v_rcp_f32_e32 v167, v168
	v_mul_f32_e32 v173, 0xbfb8aa3b, v173
	v_exp_f32_e32 v173, v173
	global_store_dwordx4 v[160:161], v[182:185], off
	s_nop 1
	v_add_f32_e32 v172, 1.0, v173
	v_add_f32_e32 v181, v116, v140
	v_rcp_f32_e32 v168, v169
	v_mul_f32_e32 v181, 0xbfb8aa3b, v181
	v_exp_f32_e32 v181, v181
	s_nop 0
	v_add_f32_e32 v173, 1.0, v181
	v_add_f32_e32 v182, v121, v145
	v_rcp_f32_e32 v169, v172
	v_mul_f32_e32 v182, 0xbfb8aa3b, v182
	v_exp_f32_e32 v182, v182
	s_nop 0
	v_add_f32_e32 v181, 1.0, v182
	v_add_f32_e32 v183, v117, v141
	v_rcp_f32_e32 v172, v173
	v_mul_f32_e32 v183, 0xbfb8aa3b, v183
	v_exp_f32_e32 v183, v183
	s_nop 0
	v_add_f32_e32 v182, 1.0, v183
	v_rcp_f32_e32 v173, v181
	v_rcp_f32_e32 v181, v182
	v_add_f32_e32 v182, v110, v142
	v_mul_f32_e32 v182, 0xbfb8aa3b, v182
	v_exp_f32_e32 v184, v182
	v_cvt_pk_bf16_f32 v182, v154, v167
	v_cvt_pk_bf16_f32 v183, v169, v173
	v_cvt_pk_bf16_f32 v185, v172, v181
	v_add_f32_e32 v172, v106, v138
	v_add_f32_e32 v154, 1.0, v184
	v_cvt_pk_bf16_f32 v184, v163, v168
	v_mul_f32_e32 v172, 0xbfb8aa3b, v172
	v_exp_f32_e32 v172, v172
	s_nop 0
	v_add_f32_e32 v167, 1.0, v172
	v_add_f32_e32 v169, v111, v143
	v_mul_f32_e32 v169, 0xbfb8aa3b, v169
	v_rcp_f32_e32 v154, v154
	v_exp_f32_e32 v169, v169
	s_nop 0
	v_add_f32_e32 v169, 1.0, v169
	v_add_f32_e32 v173, v107, v139
	v_ashrrev_i32_e32 v165, 31, v164
	v_rcp_f32_e32 v163, v167
	v_mul_f32_e32 v173, 0xbfb8aa3b, v173
	v_lshlrev_b64 v[164:165], 11, v[164:165]
	v_exp_f32_e32 v173, v173
	v_lshl_add_u64 v[164:165], v[170:171], 0, v[164:165]
	global_store_dwordx4 v[164:165], v[182:185], off
	s_nop 1
	v_add_f32_e32 v172, 1.0, v173
	v_rcp_f32_e32 v181, v169
	v_add_f32_e32 v169, v112, v144
	v_mul_f32_e32 v169, 0xbfb8aa3b, v169
	v_exp_f32_e32 v169, v169
	s_nop 0
	v_add_f32_e32 v169, 1.0, v169
	v_add_f32_e32 v182, v108, v140
	v_rcp_f32_e32 v172, v172
	v_mul_f32_e32 v182, 0xbfb8aa3b, v182
	v_exp_f32_e32 v182, v182
	s_nop 0
	v_add_f32_e32 v173, 1.0, v182
	v_rcp_f32_e32 v183, v169
	v_add_f32_e32 v169, v113, v145
	v_mul_f32_e32 v169, 0xbfb8aa3b, v169
	v_exp_f32_e32 v169, v169
	s_nop 0
	v_add_f32_e32 v169, 1.0, v169
	v_add_f32_e32 v184, v109, v141
	v_rcp_f32_e32 v173, v173
	v_mul_f32_e32 v184, 0xbfb8aa3b, v184
	v_exp_f32_e32 v184, v184
	s_nop 0
	v_add_f32_e32 v182, 1.0, v184
	v_rcp_f32_e32 v185, v169
	s_nop 0
	v_cvt_pk_bf16_f32 v183, v183, v185
	v_add_f32_e32 v168, v102, v142
	v_mul_f32_e32 v168, 0xbfb8aa3b, v168
	v_exp_f32_e32 v184, v168
	v_rcp_f32_e32 v186, v182
	v_ashrrev_i32_e32 v167, 31, v166
	v_lshlrev_b64 v[166:167], 11, v[166:167]
	v_cvt_pk_bf16_f32 v182, v154, v181
	v_add_f32_e32 v154, 1.0, v184
	v_lshl_add_u64 v[168:169], v[170:171], 0, v[166:167]
	v_cvt_pk_bf16_f32 v185, v173, v186
	v_add_f32_e32 v173, v98, v138
	v_cvt_pk_bf16_f32 v184, v163, v172
	v_mul_f32_e32 v173, 0xbfb8aa3b, v173
	v_exp_f32_e32 v173, v173
	s_nop 0
	v_add_f32_e32 v166, 1.0, v173
	v_add_f32_e32 v172, v103, v143
	v_mul_f32_e32 v172, 0xbfb8aa3b, v172
	v_rcp_f32_e32 v154, v154
	v_exp_f32_e32 v172, v172
	global_store_dwordx4 v[168:169], v[182:185], off
	v_add_f32_e32 v172, 1.0, v172
	s_nop 0
	v_add_f32_e32 v181, v99, v139
	v_rcp_f32_e32 v166, v166
	v_mul_f32_e32 v181, 0xbfb8aa3b, v181
	v_exp_f32_e32 v181, v181
	s_nop 0
	v_add_f32_e32 v173, 1.0, v181
	v_add_f32_e32 v182, v104, v144
	v_rcp_f32_e32 v167, v172
	v_mul_f32_e32 v182, 0xbfb8aa3b, v182
	v_exp_f32_e32 v182, v182
	s_nop 0
	v_add_f32_e32 v181, 1.0, v182
	v_rcp_f32_e32 v185, v173
	v_add_f32_e32 v173, v100, v140
	v_mul_f32_e32 v173, 0xbfb8aa3b, v173
	v_exp_f32_e32 v173, v173
	s_nop 0
	v_add_f32_e32 v173, 1.0, v173
	v_add_f32_e32 v184, v105, v145
	v_rcp_f32_e32 v181, v181
	v_mul_f32_e32 v184, 0xbfb8aa3b, v184
	v_exp_f32_e32 v184, v184
	s_nop 0
	v_add_f32_e32 v182, 1.0, v184
	v_rcp_f32_e32 v187, v173
	v_add_f32_e32 v173, v101, v141
	v_mul_f32_e32 v173, 0xbfb8aa3b, v173
	v_exp_f32_e32 v173, v173
	s_nop 0
	v_add_f32_e32 v173, 1.0, v173
	v_rcp_f32_e32 v186, v182
	v_add_f32_e32 v172, v94, v142
	v_mul_f32_e32 v172, 0xbfb8aa3b, v172
	v_exp_f32_e32 v184, v172
	v_rcp_f32_e32 v188, v173
	v_ashrrev_i32_e32 v163, 31, v162
	v_lshlrev_b64 v[162:163], 11, v[162:163]
	v_cvt_pk_bf16_f32 v182, v154, v167
	v_add_f32_e32 v154, 1.0, v184
	v_lshl_add_u64 v[172:173], v[170:171], 0, v[162:163]
	v_add_f32_e32 v170, v90, v138
	v_cvt_pk_bf16_f32 v184, v166, v185
	v_mul_f32_e32 v170, 0xbfb8aa3b, v170
	v_exp_f32_e32 v170, v170
	s_nop 0
	v_add_f32_e32 v166, 1.0, v170
	v_add_f32_e32 v167, v95, v143
	v_mul_f32_e32 v167, 0xbfb8aa3b, v167
	v_rcp_f32_e32 v154, v154
	v_exp_f32_e32 v167, v167
	v_cvt_pk_bf16_f32 v183, v181, v186
	v_add_f32_e32 v167, 1.0, v167
	v_add_f32_e32 v171, v91, v139
	v_rcp_f32_e32 v166, v166
	v_mul_f32_e32 v171, 0xbfb8aa3b, v171
	v_exp_f32_e32 v171, v171
	v_cvt_pk_bf16_f32 v185, v187, v188
	global_store_dwordx4 v[172:173], v[182:185], off
	s_nop 1
	v_add_f32_e32 v170, 1.0, v171
	v_add_f32_e32 v181, v96, v144
	v_rcp_f32_e32 v167, v167
	v_mul_f32_e32 v181, 0xbfb8aa3b, v181
	v_exp_f32_e32 v181, v181
	s_nop 0
	v_add_f32_e32 v171, 1.0, v181
	v_add_f32_e32 v182, v92, v140
	v_rcp_f32_e32 v170, v170
	v_mul_f32_e32 v182, 0xbfb8aa3b, v182
	v_exp_f32_e32 v182, v182
	s_nop 0
	v_add_f32_e32 v181, 1.0, v182
	v_add_f32_e32 v183, v97, v145
	v_rcp_f32_e32 v171, v171
	v_mul_f32_e32 v183, 0xbfb8aa3b, v183
	v_exp_f32_e32 v183, v183
	s_nop 0
	v_add_f32_e32 v182, 1.0, v183
	v_add_f32_e32 v184, v93, v141
	v_rcp_f32_e32 v181, v181
	v_mul_f32_e32 v184, 0xbfb8aa3b, v184
	v_exp_f32_e32 v184, v184
	s_nop 0
	v_add_f32_e32 v183, 1.0, v184
	v_rcp_f32_e32 v185, v182
	v_cvt_pk_bf16_f32 v182, v154, v167
	v_add_f32_e32 v154, v86, v142
	v_mul_f32_e32 v154, 0xbfb8aa3b, v154
	v_exp_f32_e32 v154, v154
	v_cvt_pk_bf16_f32 v184, v166, v170
	v_add_f32_e32 v154, 1.0, v154
	v_rcp_f32_e32 v186, v183
	v_cvt_pk_bf16_f32 v183, v171, v185
	v_add_co_u32_e32 v166, vcc, s90, v160
	v_cvt_pk_bf16_f32 v185, v181, v186
	v_add_f32_e32 v181, v82, v138
	s_nop 0
	v_addc_co_u32_e32 v167, vcc, 0, v161, vcc
	global_store_dwordx4 v[166:167], v[182:185], off
	v_mul_f32_e32 v181, 0xbfb8aa3b, v181
	v_exp_f32_e32 v181, v181
	s_nop 0
	v_add_f32_e32 v170, 1.0, v181
	v_add_f32_e32 v171, v87, v143
	v_mul_f32_e32 v171, 0xbfb8aa3b, v171
	v_rcp_f32_e32 v154, v154
	v_exp_f32_e32 v171, v171
	s_nop 0
	v_add_f32_e32 v171, 1.0, v171
	v_add_f32_e32 v182, v83, v139
	v_rcp_f32_e32 v170, v170
	v_mul_f32_e32 v182, 0xbfb8aa3b, v182
	v_exp_f32_e32 v182, v182
	s_nop 0
	v_add_f32_e32 v181, 1.0, v182
	v_add_f32_e32 v183, v88, v144
	v_rcp_f32_e32 v171, v171
	v_mul_f32_e32 v183, 0xbfb8aa3b, v183
	v_exp_f32_e32 v183, v183
	s_nop 0
	v_add_f32_e32 v182, 1.0, v183
	v_add_f32_e32 v184, v84, v140
	v_rcp_f32_e32 v181, v181
	v_mul_f32_e32 v184, 0xbfb8aa3b, v184
	v_exp_f32_e32 v184, v184
	s_nop 0
	v_add_f32_e32 v183, 1.0, v184
	v_rcp_f32_e32 v185, v182
	v_add_f32_e32 v182, v89, v145
	v_mul_f32_e32 v182, 0xbfb8aa3b, v182
	v_exp_f32_e32 v182, v182
	s_nop 0
	v_add_f32_e32 v182, 1.0, v182
	v_rcp_f32_e32 v186, v183
	v_add_f32_e32 v183, v85, v141
	v_mul_f32_e32 v183, 0xbfb8aa3b, v183
	v_exp_f32_e32 v183, v183
	s_nop 0
	v_add_f32_e32 v183, 1.0, v183
	v_rcp_f32_e32 v187, v182
	v_lshl_add_u64 v[162:163], v[160:161], 0, s[34:35]
	v_cvt_pk_bf16_f32 v182, v154, v171
	v_add_f32_e32 v154, v78, v142
	v_mul_f32_e32 v154, 0xbfb8aa3b, v154
	v_exp_f32_e32 v154, v154
	v_cvt_pk_bf16_f32 v184, v170, v181
	v_add_f32_e32 v154, 1.0, v154
	v_rcp_f32_e32 v188, v183
	v_cvt_pk_bf16_f32 v183, v185, v187
	v_cvt_pk_bf16_f32 v185, v186, v188
	v_add_co_u32_e32 v170, vcc, s91, v160
	v_add_f32_e32 v142, v70, v142
	s_nop 0
	v_addc_co_u32_e32 v171, vcc, 0, v161, vcc
	global_store_dwordx4 v[170:171], v[182:185], off
	s_nop 1
	v_add_f32_e32 v182, v74, v138
	v_mul_f32_e32 v182, 0xbfb8aa3b, v182
	v_exp_f32_e32 v182, v182
	s_nop 0
	v_add_f32_e32 v181, 1.0, v182
	v_add_f32_e32 v184, v79, v143
	v_rcp_f32_e32 v154, v154
	v_mul_f32_e32 v184, 0xbfb8aa3b, v184
	v_exp_f32_e32 v184, v184
	s_nop 0
	v_add_f32_e32 v182, 1.0, v184
	v_add_f32_e32 v183, v75, v139
	v_mul_f32_e32 v183, 0xbfb8aa3b, v183
	v_rcp_f32_e32 v181, v181
	v_exp_f32_e32 v183, v183
	s_nop 0
	v_add_f32_e32 v183, 1.0, v183
	v_add_f32_e32 v185, v80, v144
	v_rcp_f32_e32 v182, v182
	v_mul_f32_e32 v185, 0xbfb8aa3b, v185
	v_exp_f32_e32 v185, v185
	s_nop 0
	v_add_f32_e32 v184, 1.0, v185
	v_rcp_f32_e32 v186, v183
	v_add_f32_e32 v183, v76, v140
	v_mul_f32_e32 v183, 0xbfb8aa3b, v183
	v_exp_f32_e32 v183, v183
	s_nop 0
	v_add_f32_e32 v183, 1.0, v183
	v_add_f32_e32 v187, v81, v145
	v_rcp_f32_e32 v184, v184
	v_mul_f32_e32 v187, 0xbfb8aa3b, v187
	v_exp_f32_e32 v187, v187
	s_nop 0
	v_add_f32_e32 v185, 1.0, v187
	v_rcp_f32_e32 v188, v183
	v_add_f32_e32 v183, v77, v141
	v_mul_f32_e32 v183, 0xbfb8aa3b, v183
	v_exp_f32_e32 v183, v183
	s_nop 0
	v_add_f32_e32 v183, 1.0, v183
	v_rcp_f32_e32 v185, v185
	v_mul_f32_e32 v142, 0xbfb8aa3b, v142
	v_exp_f32_e32 v142, v142
	s_nop 0
	v_add_f32_e32 v142, 1.0, v142
	v_cvt_pk_bf16_f32 v182, v154, v182
	v_rcp_f32_e32 v187, v183
	v_cvt_pk_bf16_f32 v183, v184, v185
	v_cvt_pk_bf16_f32 v184, v181, v186
	v_add_co_u32_e32 v186, vcc, s92, v160
	v_add_f32_e32 v138, v66, v138
	v_cvt_pk_bf16_f32 v185, v188, v187
	s_nop 0
	v_addc_co_u32_e32 v187, vcc, 0, v161, vcc
	v_mul_f32_e32 v138, 0xbfb8aa3b, v138
	global_store_dwordx4 v[186:187], v[182:185], off
	v_exp_f32_e32 v138, v138
	v_add_f32_e32 v143, v71, v143
	v_add_f32_e32 v138, 1.0, v138
	v_mul_f32_e32 v143, 0xbfb8aa3b, v143
	v_rcp_f32_e32 v142, v142
	v_exp_f32_e32 v143, v143
	s_nop 0
	v_add_f32_e32 v143, 1.0, v143
	v_add_f32_e32 v139, v67, v139
	v_mul_f32_e32 v139, 0xbfb8aa3b, v139
	v_rcp_f32_e32 v154, v138
	v_exp_f32_e32 v139, v139
	s_nop 0
	v_add_f32_e32 v139, 1.0, v139
	v_add_f32_e32 v144, v72, v144
	v_mul_f32_e32 v144, 0xbfb8aa3b, v144
	v_rcp_f32_e32 v143, v143
	v_exp_f32_e32 v144, v144
	s_nop 0
	v_add_f32_e32 v144, 1.0, v144
	v_add_f32_e32 v140, v68, v140
	v_mul_f32_e32 v140, 0xbfb8aa3b, v140
	v_rcp_f32_e32 v181, v139
	v_exp_f32_e32 v140, v140
	s_nop 0
	v_add_f32_e32 v140, 1.0, v140
	v_add_f32_e32 v145, v73, v145
	v_mul_f32_e32 v145, 0xbfb8aa3b, v145
	v_rcp_f32_e32 v144, v144
	v_exp_f32_e32 v145, v145
	s_nop 0
	v_add_f32_e32 v145, 1.0, v145
	v_rcp_f32_e32 v184, v140
	v_add_f32_e32 v140, v69, v141
	v_mul_f32_e32 v140, 0xbfb8aa3b, v140
	v_exp_f32_e32 v140, v140
	s_nop 0
	v_add_f32_e32 v140, 1.0, v140
	v_rcp_f32_e32 v145, v145
	v_lshl_add_u64 v[166:167], v[160:161], 0, s[36:37]
	v_add_f32_e32 v141, v62, v134
	v_mul_f32_e32 v141, 0xbfb8aa3b, v141
	v_exp_f32_e32 v183, v141
	v_rcp_f32_e32 v182, v140
	v_cvt_pk_bf16_f32 v140, v142, v143
	v_cvt_pk_bf16_f32 v142, v154, v181
	v_add_f32_e32 v154, 1.0, v183
	v_cvt_pk_bf16_f32 v141, v144, v145
	v_add_co_u32_e32 v144, vcc, s93, v160
	v_cvt_pk_bf16_f32 v143, v184, v182
	s_nop 0
	v_addc_co_u32_e32 v145, vcc, 0, v161, vcc
	global_store_dwordx4 v[144:145], v[140:143], off
	v_lshl_add_u64 v[170:171], v[160:161], 0, s[38:39]
	v_lshl_add_u64 v[138:139], v[160:161], 0, s[40:41]
	v_add_f32_e32 v142, v58, v130
	v_mul_f32_e32 v142, 0xbfb8aa3b, v142
	v_exp_f32_e32 v142, v142
	s_nop 0
	v_add_f32_e32 v142, 1.0, v142
	v_rcp_f32_e32 v140, v154
	v_add_f32_e32 v154, v63, v135
	v_mul_f32_e32 v154, 0xbfb8aa3b, v154
	v_exp_f32_e32 v154, v154
	s_nop 0
	v_add_f32_e32 v143, 1.0, v154
	v_add_f32_e32 v145, v59, v131
	v_mul_f32_e32 v145, 0xbfb8aa3b, v145
	v_rcp_f32_e32 v142, v142
	v_exp_f32_e32 v145, v145
	s_nop 0
	v_add_f32_e32 v145, 1.0, v145
	v_add_f32_e32 v181, v64, v136
	v_rcp_f32_e32 v141, v143
	v_mul_f32_e32 v181, 0xbfb8aa3b, v181
	v_exp_f32_e32 v181, v181
	s_nop 0
	v_add_f32_e32 v154, 1.0, v181
	v_add_f32_e32 v182, v60, v132
	v_mul_f32_e32 v182, 0xbfb8aa3b, v182
	v_exp_f32_e32 v182, v182
	v_rcp_f32_e32 v143, v145
	v_add_f32_e32 v181, 1.0, v182
	v_add_f32_e32 v183, v65, v137
	v_mul_f32_e32 v183, 0xbfb8aa3b, v183
	v_exp_f32_e32 v183, v183
	v_rcp_f32_e32 v144, v154
	v_add_f32_e32 v182, 1.0, v183
	v_add_f32_e32 v184, v61, v133
	v_mul_f32_e32 v184, 0xbfb8aa3b, v184
	v_exp_f32_e32 v184, v184
	v_rcp_f32_e32 v145, v181
	v_add_f32_e32 v183, 1.0, v184
	v_rcp_f32_e32 v154, v182
	v_cvt_pk_bf16_f32 v140, v140, v141
	v_add_f32_e32 v182, v54, v134
	v_mul_f32_e32 v182, 0xbfb8aa3b, v182
	v_exp_f32_e32 v182, v182
	v_cvt_pk_bf16_f32 v141, v144, v154
	v_cvt_pk_bf16_f32 v142, v142, v143
	v_rcp_f32_e32 v181, v183
	v_add_f32_e32 v144, 1.0, v182
	v_cvt_pk_bf16_f32 v143, v145, v181
	global_store_dwordx4 v[160:161], v[140:143], off offset:256
	s_nop 1
	v_add_f32_e32 v142, v50, v130
	v_mul_f32_e32 v142, 0xbfb8aa3b, v142
	v_exp_f32_e32 v142, v142
	s_nop 0
	v_add_f32_e32 v142, 1.0, v142
	v_add_f32_e32 v154, v55, v135
	v_mul_f32_e32 v154, 0xbfb8aa3b, v154
	v_exp_f32_e32 v154, v154
	v_rcp_f32_e32 v140, v144
	v_add_f32_e32 v143, 1.0, v154
	v_add_f32_e32 v145, v51, v131
	v_mul_f32_e32 v145, 0xbfb8aa3b, v145
	v_rcp_f32_e32 v142, v142
	v_exp_f32_e32 v145, v145
	s_nop 0
	v_add_f32_e32 v145, 1.0, v145
	v_add_f32_e32 v160, v56, v136
	v_rcp_f32_e32 v141, v143
	v_mul_f32_e32 v160, 0xbfb8aa3b, v160
	v_exp_f32_e32 v160, v160
	s_nop 0
	v_add_f32_e32 v154, 1.0, v160
	v_add_f32_e32 v161, v52, v132
	v_mul_f32_e32 v161, 0xbfb8aa3b, v161
	v_exp_f32_e32 v161, v161
	v_rcp_f32_e32 v143, v145
	v_add_f32_e32 v160, 1.0, v161
	v_add_f32_e32 v181, v57, v137
	v_mul_f32_e32 v181, 0xbfb8aa3b, v181
	v_exp_f32_e32 v181, v181
	v_rcp_f32_e32 v144, v154
	v_add_f32_e32 v161, 1.0, v181
	v_add_f32_e32 v182, v53, v133
	v_mul_f32_e32 v182, 0xbfb8aa3b, v182
	v_exp_f32_e32 v182, v182
	v_rcp_f32_e32 v145, v160
	v_add_f32_e32 v181, 1.0, v182
	v_rcp_f32_e32 v154, v161
	v_cvt_pk_bf16_f32 v140, v140, v141
	v_add_f32_e32 v161, v46, v134
	v_mul_f32_e32 v161, 0xbfb8aa3b, v161
	v_exp_f32_e32 v161, v161
	v_cvt_pk_bf16_f32 v141, v144, v154
	v_cvt_pk_bf16_f32 v142, v142, v143
	v_rcp_f32_e32 v160, v181
	v_add_f32_e32 v144, 1.0, v161
	v_cvt_pk_bf16_f32 v143, v145, v160
	global_store_dwordx4 v[164:165], v[140:143], off offset:256
	s_nop 1
	v_add_f32_e32 v142, v42, v130
	v_mul_f32_e32 v142, 0xbfb8aa3b, v142
	v_exp_f32_e32 v142, v142
	s_nop 0
	v_add_f32_e32 v142, 1.0, v142
	v_add_f32_e32 v154, v47, v135
	v_mul_f32_e32 v154, 0xbfb8aa3b, v154
	v_exp_f32_e32 v154, v154
	v_rcp_f32_e32 v140, v144
	v_add_f32_e32 v143, 1.0, v154
	v_add_f32_e32 v145, v43, v131
	v_mul_f32_e32 v145, 0xbfb8aa3b, v145
	v_rcp_f32_e32 v142, v142
	v_exp_f32_e32 v145, v145
	s_nop 0
	v_add_f32_e32 v145, 1.0, v145
	v_add_f32_e32 v160, v48, v136
	v_rcp_f32_e32 v141, v143
	v_mul_f32_e32 v160, 0xbfb8aa3b, v160
	v_exp_f32_e32 v160, v160
	s_nop 0
	v_add_f32_e32 v154, 1.0, v160
	v_add_f32_e32 v161, v44, v132
	v_mul_f32_e32 v161, 0xbfb8aa3b, v161
	v_exp_f32_e32 v161, v161
	v_rcp_f32_e32 v143, v145
	v_add_f32_e32 v160, 1.0, v161
	v_add_f32_e32 v164, v49, v137
	v_mul_f32_e32 v164, 0xbfb8aa3b, v164
	v_exp_f32_e32 v164, v164
	v_rcp_f32_e32 v144, v154
	v_add_f32_e32 v161, 1.0, v164
	v_add_f32_e32 v165, v45, v133
	v_mul_f32_e32 v165, 0xbfb8aa3b, v165
	v_exp_f32_e32 v165, v165
	v_rcp_f32_e32 v145, v160
	v_add_f32_e32 v164, 1.0, v165
	v_rcp_f32_e32 v154, v161
	v_cvt_pk_bf16_f32 v140, v140, v141
	v_add_f32_e32 v161, v38, v134
	v_mul_f32_e32 v161, 0xbfb8aa3b, v161
	v_exp_f32_e32 v161, v161
	v_cvt_pk_bf16_f32 v141, v144, v154
	v_cvt_pk_bf16_f32 v142, v142, v143
	v_rcp_f32_e32 v160, v164
	v_add_f32_e32 v144, 1.0, v161
	v_cvt_pk_bf16_f32 v143, v145, v160
	global_store_dwordx4 v[168:169], v[140:143], off offset:256
	s_nop 1
	v_add_f32_e32 v142, v34, v130
	v_mul_f32_e32 v142, 0xbfb8aa3b, v142
	v_exp_f32_e32 v142, v142
	s_nop 0
	v_add_f32_e32 v142, 1.0, v142
	v_add_f32_e32 v154, v39, v135
	v_mul_f32_e32 v154, 0xbfb8aa3b, v154
	v_exp_f32_e32 v154, v154
	v_rcp_f32_e32 v140, v144
	v_add_f32_e32 v143, 1.0, v154
	v_add_f32_e32 v145, v35, v131
	v_mul_f32_e32 v145, 0xbfb8aa3b, v145
	v_rcp_f32_e32 v142, v142
	v_exp_f32_e32 v145, v145
	s_nop 0
	v_add_f32_e32 v145, 1.0, v145
	v_add_f32_e32 v160, v40, v136
	v_rcp_f32_e32 v141, v143
	v_mul_f32_e32 v160, 0xbfb8aa3b, v160
	v_exp_f32_e32 v160, v160
	s_nop 0
	v_add_f32_e32 v154, 1.0, v160
	v_add_f32_e32 v161, v36, v132
	v_mul_f32_e32 v161, 0xbfb8aa3b, v161
	v_exp_f32_e32 v161, v161
	v_rcp_f32_e32 v143, v145
	v_add_f32_e32 v160, 1.0, v161
	v_add_f32_e32 v164, v41, v137
	v_mul_f32_e32 v164, 0xbfb8aa3b, v164
	v_exp_f32_e32 v164, v164
	v_rcp_f32_e32 v144, v154
	v_add_f32_e32 v161, 1.0, v164
	v_add_f32_e32 v165, v37, v133
	v_mul_f32_e32 v165, 0xbfb8aa3b, v165
	v_exp_f32_e32 v165, v165
	v_rcp_f32_e32 v145, v160
	v_add_f32_e32 v164, 1.0, v165
	v_rcp_f32_e32 v154, v161
	v_cvt_pk_bf16_f32 v140, v140, v141
	v_add_f32_e32 v161, v30, v134
	v_mul_f32_e32 v161, 0xbfb8aa3b, v161
	v_exp_f32_e32 v161, v161
	v_cvt_pk_bf16_f32 v141, v144, v154
	v_cvt_pk_bf16_f32 v142, v142, v143
	v_rcp_f32_e32 v160, v164
	v_add_f32_e32 v144, 1.0, v161
	v_cvt_pk_bf16_f32 v143, v145, v160
	global_store_dwordx4 v[172:173], v[140:143], off offset:256
	s_nop 1
	v_add_f32_e32 v142, v26, v130
	v_mul_f32_e32 v142, 0xbfb8aa3b, v142
	v_exp_f32_e32 v142, v142
	s_nop 0
	v_add_f32_e32 v142, 1.0, v142
	v_add_f32_e32 v154, v31, v135
	v_mul_f32_e32 v154, 0xbfb8aa3b, v154
	v_exp_f32_e32 v154, v154
	v_rcp_f32_e32 v140, v144
	v_add_f32_e32 v143, 1.0, v154
	v_add_f32_e32 v145, v27, v131
	v_mul_f32_e32 v145, 0xbfb8aa3b, v145
	v_rcp_f32_e32 v142, v142
	v_exp_f32_e32 v145, v145
	s_nop 0
	v_add_f32_e32 v145, 1.0, v145
	v_add_f32_e32 v160, v32, v136
	v_rcp_f32_e32 v141, v143
	v_mul_f32_e32 v160, 0xbfb8aa3b, v160
	v_exp_f32_e32 v160, v160
	s_nop 0
	v_add_f32_e32 v154, 1.0, v160
	v_add_f32_e32 v161, v28, v132
	v_mul_f32_e32 v161, 0xbfb8aa3b, v161
	v_exp_f32_e32 v161, v161
	v_rcp_f32_e32 v143, v145
	v_add_f32_e32 v160, 1.0, v161
	v_add_f32_e32 v164, v33, v137
	v_mul_f32_e32 v164, 0xbfb8aa3b, v164
	v_exp_f32_e32 v164, v164
	v_rcp_f32_e32 v144, v154
	v_add_f32_e32 v161, 1.0, v164
	v_add_f32_e32 v165, v29, v133
	v_mul_f32_e32 v165, 0xbfb8aa3b, v165
	v_exp_f32_e32 v165, v165
	v_rcp_f32_e32 v145, v160
	v_add_f32_e32 v164, 1.0, v165
	v_rcp_f32_e32 v154, v161
	v_cvt_pk_bf16_f32 v140, v140, v141
	v_add_f32_e32 v161, v22, v134
	v_mul_f32_e32 v161, 0xbfb8aa3b, v161
	v_exp_f32_e32 v161, v161
	v_cvt_pk_bf16_f32 v141, v144, v154
	v_cvt_pk_bf16_f32 v142, v142, v143
	v_rcp_f32_e32 v160, v164
	v_add_f32_e32 v144, 1.0, v161
	v_cvt_pk_bf16_f32 v143, v145, v160
	global_store_dwordx4 v[162:163], v[140:143], off offset:256
	s_nop 1
	v_add_f32_e32 v142, v18, v130
	v_mul_f32_e32 v142, 0xbfb8aa3b, v142
	v_exp_f32_e32 v142, v142
	s_nop 0
	v_add_f32_e32 v142, 1.0, v142
	v_add_f32_e32 v154, v23, v135
	v_mul_f32_e32 v154, 0xbfb8aa3b, v154
	v_exp_f32_e32 v154, v154
	v_rcp_f32_e32 v140, v144
	v_add_f32_e32 v143, 1.0, v154
	v_add_f32_e32 v145, v19, v131
	v_mul_f32_e32 v145, 0xbfb8aa3b, v145
	v_rcp_f32_e32 v142, v142
	v_exp_f32_e32 v145, v145
	s_nop 0
	v_add_f32_e32 v145, 1.0, v145
	v_add_f32_e32 v160, v24, v136
	v_rcp_f32_e32 v141, v143
	v_mul_f32_e32 v160, 0xbfb8aa3b, v160
	v_exp_f32_e32 v160, v160
	s_nop 0
	v_add_f32_e32 v154, 1.0, v160
	v_add_f32_e32 v161, v20, v132
	v_mul_f32_e32 v161, 0xbfb8aa3b, v161
	v_exp_f32_e32 v161, v161
	v_rcp_f32_e32 v143, v145
	v_add_f32_e32 v160, 1.0, v161
	v_add_f32_e32 v162, v25, v137
	v_mul_f32_e32 v162, 0xbfb8aa3b, v162
	v_exp_f32_e32 v162, v162
	v_rcp_f32_e32 v144, v154
	v_add_f32_e32 v161, 1.0, v162
	v_add_f32_e32 v163, v21, v133
	v_mul_f32_e32 v163, 0xbfb8aa3b, v163
	v_exp_f32_e32 v163, v163
	v_rcp_f32_e32 v145, v160
	v_add_f32_e32 v162, 1.0, v163
	v_rcp_f32_e32 v154, v161
	v_cvt_pk_bf16_f32 v140, v140, v141
	v_add_f32_e32 v161, v14, v134
	v_mul_f32_e32 v161, 0xbfb8aa3b, v161
	v_exp_f32_e32 v161, v161
	v_cvt_pk_bf16_f32 v141, v144, v154
	v_cvt_pk_bf16_f32 v142, v142, v143
	v_rcp_f32_e32 v160, v162
	v_add_f32_e32 v144, 1.0, v161
	v_cvt_pk_bf16_f32 v143, v145, v160
	global_store_dwordx4 v[166:167], v[140:143], off offset:256
	v_add_f32_e32 v134, v6, v134
	v_mul_f32_e32 v134, 0xbfb8aa3b, v134
	v_add_f32_e32 v142, v10, v130
	v_mul_f32_e32 v142, 0xbfb8aa3b, v142
	v_exp_f32_e32 v142, v142
	s_nop 0
	v_add_f32_e32 v142, 1.0, v142
	v_add_f32_e32 v154, v15, v135
	v_mul_f32_e32 v154, 0xbfb8aa3b, v154
	v_exp_f32_e32 v154, v154
	v_rcp_f32_e32 v140, v144
	v_add_f32_e32 v143, 1.0, v154
	v_add_f32_e32 v145, v11, v131
	v_mul_f32_e32 v145, 0xbfb8aa3b, v145
	v_rcp_f32_e32 v142, v142
	v_exp_f32_e32 v145, v145
	s_nop 0
	v_add_f32_e32 v145, 1.0, v145
	v_add_f32_e32 v160, v16, v136
	v_rcp_f32_e32 v141, v143
	v_mul_f32_e32 v160, 0xbfb8aa3b, v160
	v_exp_f32_e32 v160, v160
	s_nop 0
	v_add_f32_e32 v154, 1.0, v160
	v_add_f32_e32 v161, v12, v132
	v_mul_f32_e32 v161, 0xbfb8aa3b, v161
	v_exp_f32_e32 v161, v161
	v_rcp_f32_e32 v143, v145
	v_add_f32_e32 v160, 1.0, v161
	v_add_f32_e32 v162, v17, v137
	v_mul_f32_e32 v162, 0xbfb8aa3b, v162
	v_exp_f32_e32 v162, v162
	v_rcp_f32_e32 v144, v154
	v_add_f32_e32 v161, 1.0, v162
	v_add_f32_e32 v163, v13, v133
	v_mul_f32_e32 v163, 0xbfb8aa3b, v163
	v_exp_f32_e32 v163, v163
	v_rcp_f32_e32 v145, v160
	v_add_f32_e32 v162, 1.0, v163
	v_exp_f32_e32 v134, v134
	v_rcp_f32_e32 v154, v161
	v_add_f32_e32 v134, 1.0, v134
	v_cvt_pk_bf16_f32 v140, v140, v141
	v_cvt_pk_bf16_f32 v141, v144, v154
	v_add_f32_e32 v130, v2, v130
	v_mul_f32_e32 v130, 0xbfb8aa3b, v130
	v_exp_f32_e32 v130, v130
	v_rcp_f32_e32 v160, v162
	v_cvt_pk_bf16_f32 v142, v142, v143
	v_cvt_pk_bf16_f32 v143, v145, v160
	global_store_dwordx4 v[170:171], v[140:143], off offset:256
	v_add_f32_e32 v130, 1.0, v130
	v_add_f32_e32 v135, v7, v135
	v_mul_f32_e32 v135, 0xbfb8aa3b, v135
	v_rcp_f32_e32 v134, v134
	v_exp_f32_e32 v135, v135
	s_nop 0
	v_add_f32_e32 v135, 1.0, v135
	v_add_f32_e32 v131, v3, v131
	v_mul_f32_e32 v131, 0xbfb8aa3b, v131
	v_rcp_f32_e32 v140, v130
	v_exp_f32_e32 v131, v131
	s_nop 0
	v_add_f32_e32 v131, 1.0, v131
	v_add_f32_e32 v136, v8, v136
	v_mul_f32_e32 v136, 0xbfb8aa3b, v136
	v_rcp_f32_e32 v130, v135
	v_exp_f32_e32 v136, v136
	s_nop 0
	v_add_f32_e32 v136, 1.0, v136
	v_add_f32_e32 v132, v4, v132
	v_mul_f32_e32 v132, 0xbfb8aa3b, v132
	v_rcp_f32_e32 v135, v131
	v_exp_f32_e32 v132, v132
	s_nop 0
	v_add_f32_e32 v132, 1.0, v132
	v_add_f32_e32 v137, v9, v137
	v_mul_f32_e32 v137, 0xbfb8aa3b, v137
	v_rcp_f32_e32 v131, v136
	v_exp_f32_e32 v137, v137
	s_nop 0
	v_add_f32_e32 v137, 1.0, v137
	v_add_f32_e32 v133, v5, v133
	v_mul_f32_e32 v133, 0xbfb8aa3b, v133
	v_rcp_f32_e32 v136, v132
	v_exp_f32_e32 v133, v133
	s_nop 0
	v_add_f32_e32 v133, 1.0, v133
	v_rcp_f32_e32 v132, v137
	v_cvt_pk_bf16_f32 v130, v134, v130
	v_rcp_f32_e32 v133, v133
	v_cvt_pk_bf16_f32 v131, v131, v132
	v_cvt_pk_bf16_f32 v132, v140, v135
	v_cvt_pk_bf16_f32 v133, v136, v133
	global_store_dwordx4 v[138:139], v[130:133], off offset:256

.LBB0_1011:
	s_lshl_b32 s0, s94, 8
	s_and_b32 s0, s0, 0x300
	v_or_b32_e32 v132, s0, v175
	v_lshlrev_b32_e32 v154, 2, v132
	v_lshl_add_u64 v[130:131], s[16:17], 0, v[154:155]
	flat_load_dwordx4 v[142:145], v[130:131]
	flat_load_dwordx4 v[138:141], v[130:131] offset:16
	v_lshlrev_b32_e32 v154, 1, v132
	v_lshl_add_u64 v[160:161], s[30:31], 0, v[154:155]
	v_lshl_add_u32 v162, s62, 8, v1
	flat_load_dwordx4 v[134:137], v[130:131] offset:512
	s_nop 0
	flat_load_dwordx4 v[130:133], v[130:131] offset:528
	s_waitcnt vmcnt(0) lgkmcnt(0)
	v_add_f32_e32 v126, v126, v142
	v_add_f32_e32 v122, v122, v138
	v_mul_f32_e32 v126, 0xbfb8aa3b, v126
	v_add_f32_e32 v127, v127, v143
	v_mul_f32_e32 v122, 0xbfb8aa3b, v122
	v_exp_f32_e32 v126, v126
	v_add_f32_e32 v123, v123, v139
	v_mul_f32_e32 v127, 0xbfb8aa3b, v127
	v_exp_f32_e32 v122, v122
	v_mul_f32_e32 v123, 0xbfb8aa3b, v123
	v_exp_f32_e32 v127, v127
	v_exp_f32_e32 v123, v123
	v_add_f32_e32 v126, 1.0, v126
	v_add_f32_e32 v128, v128, v144
	v_add_f32_e32 v122, 1.0, v122
	v_mul_f32_e32 v128, 0xbfb8aa3b, v128
	v_add_f32_e32 v127, 1.0, v127
	v_exp_f32_e32 v128, v128
	v_add_f32_e32 v123, 1.0, v123
	v_add_f32_e32 v128, 1.0, v128
	v_add_f32_e32 v124, v124, v140
	v_mul_f32_e32 v124, 0xbfb8aa3b, v124
	v_exp_f32_e32 v124, v124
	v_rcp_f32_e32 v126, v126
	v_rcp_f32_e32 v122, v122
	v_add_f32_e32 v124, 1.0, v124
	v_mul_f32_e32 v164, 0x3f1b4598, v122
	v_rcp_f32_e32 v122, v127
	s_nop 0
	v_mul_f32_e32 v154, 0x3f1b4598, v122
	v_rcp_f32_e32 v122, v123
	s_nop 0
	v_mul_f32_e32 v127, 0x3f1b4598, v122
	v_add_f32_e32 v129, v129, v145
	v_rcp_f32_e32 v123, v128
	v_mul_f32_e32 v129, 0xbfb8aa3b, v129
	v_mul_f32_e32 v128, 0x3f1b4598, v123
	v_exp_f32_e32 v129, v129
	s_nop 0
	v_add_f32_e32 v129, 1.0, v129
	v_rcp_f32_e32 v122, v124
	v_add_f32_e32 v124, v125, v141
	v_mul_f32_e32 v124, 0xbfb8aa3b, v124
	v_exp_f32_e32 v124, v124
	v_mul_f32_e32 v167, 0x3f1b4598, v122
	v_add_f32_e32 v124, 1.0, v124
	v_add_f32_e32 v118, v118, v142
	v_rcp_f32_e32 v122, v129
	v_mul_f32_e32 v118, 0xbfb8aa3b, v118
	v_mul_f32_e32 v129, 0x3f1b4598, v122
	v_exp_f32_e32 v118, v118
	s_nop 0
	v_add_f32_e32 v118, 1.0, v118
	v_cvt_pk_bf16_f32 v125, v128, v129
	v_rcp_f32_e32 v122, v124
	v_ashrrev_i32_e32 v163, 31, v162
	v_add_f32_e32 v114, v114, v138
	v_mul_f32_e32 v165, 0x3f1b4598, v122
	v_lshlrev_b64 v[122:123], 11, v[162:163]
	v_mul_f32_e32 v114, 0xbfb8aa3b, v114
	v_mul_f32_e32 v126, 0x3f1b4598, v126
	v_lshl_add_u64 v[122:123], v[160:161], 0, v[122:123]
	v_cvt_pk_bf16_f32 v124, v126, v154
	v_exp_f32_e32 v114, v114
	v_cvt_pk_bf16_f32 v126, v164, v127
	v_cvt_pk_bf16_f32 v127, v167, v165
	global_store_dwordx4 v[122:123], v[124:127], off
	v_add_f32_e32 v114, 1.0, v114
	v_add_f32_e32 v119, v119, v143
	v_mul_f32_e32 v119, 0xbfb8aa3b, v119
	v_rcp_f32_e32 v118, v118
	v_exp_f32_e32 v119, v119
	s_nop 0
	v_add_f32_e32 v119, 1.0, v119
	v_add_f32_e32 v115, v115, v139
	v_rcp_f32_e32 v114, v114
	v_mul_f32_e32 v115, 0xbfb8aa3b, v115
	v_mul_f32_e32 v124, 0x3f1b4598, v114
	v_exp_f32_e32 v115, v115
	s_nop 0
	v_add_f32_e32 v115, 1.0, v115
	v_add_f32_e32 v120, v120, v144
	v_rcp_f32_e32 v114, v119
	v_mul_f32_e32 v120, 0xbfb8aa3b, v120
	v_mul_f32_e32 v119, 0x3f1b4598, v114
	v_exp_f32_e32 v120, v120
	s_nop 0
	v_add_f32_e32 v120, 1.0, v120
	v_add_f32_e32 v116, v116, v140
	v_rcp_f32_e32 v114, v115
	v_mul_f32_e32 v116, 0xbfb8aa3b, v116
	v_mul_f32_e32 v125, 0x3f1b4598, v114
	v_exp_f32_e32 v116, v116
	s_nop 0
	v_add_f32_e32 v116, 1.0, v116
	v_add_f32_e32 v121, v121, v145
	v_rcp_f32_e32 v114, v120
	v_mul_f32_e32 v121, 0xbfb8aa3b, v121
	v_mul_f32_e32 v120, 0x3f1b4598, v114
	v_exp_f32_e32 v121, v121
	s_nop 0
	v_add_f32_e32 v121, 1.0, v121
	v_rcp_f32_e32 v114, v116
	v_add_f32_e32 v116, v117, v141
	v_mul_f32_e32 v116, 0xbfb8aa3b, v116
	v_exp_f32_e32 v116, v116
	v_mul_f32_e32 v127, 0x3f1b4598, v114
	v_add_f32_e32 v116, 1.0, v116
	v_rcp_f32_e32 v114, v121
	s_nop 0
	v_mul_f32_e32 v121, 0x3f1b4598, v114
	v_add_f32_e32 v110, v110, v142
	v_mul_f32_e32 v110, 0xbfb8aa3b, v110
	v_exp_f32_e32 v110, v110
	s_nop 0
	v_add_f32_e32 v110, 1.0, v110
	v_rcp_f32_e32 v114, v116
	v_cvt_pk_bf16_f32 v117, v120, v121
	v_mul_f32_e32 v126, 0x3f1b4598, v114
	v_or_b32_e32 v114, 16, v162
	v_ashrrev_i32_e32 v115, 31, v114
	v_add_f32_e32 v106, v106, v138
	v_lshlrev_b64 v[114:115], 11, v[114:115]
	v_mul_f32_e32 v106, 0xbfb8aa3b, v106
	v_mul_f32_e32 v118, 0x3f1b4598, v118
	v_lshl_add_u64 v[114:115], v[160:161], 0, v[114:115]
	v_cvt_pk_bf16_f32 v116, v118, v119
	v_exp_f32_e32 v106, v106
	v_cvt_pk_bf16_f32 v118, v124, v125
	v_cvt_pk_bf16_f32 v119, v127, v126
	global_store_dwordx4 v[114:115], v[116:119], off
	v_add_f32_e32 v106, 1.0, v106
	v_add_f32_e32 v111, v111, v143
	v_mul_f32_e32 v111, 0xbfb8aa3b, v111
	v_rcp_f32_e32 v110, v110
	v_exp_f32_e32 v111, v111
	s_nop 0
	v_add_f32_e32 v111, 1.0, v111
	v_add_f32_e32 v107, v107, v139
	v_rcp_f32_e32 v106, v106
	v_mul_f32_e32 v107, 0xbfb8aa3b, v107
	v_mul_f32_e32 v116, 0x3f1b4598, v106
	v_exp_f32_e32 v107, v107
	s_nop 0
	v_add_f32_e32 v107, 1.0, v107
	v_add_f32_e32 v112, v112, v144
	v_rcp_f32_e32 v106, v111
	v_mul_f32_e32 v112, 0xbfb8aa3b, v112
	v_mul_f32_e32 v111, 0x3f1b4598, v106
	v_exp_f32_e32 v112, v112
	s_nop 0
	v_add_f32_e32 v112, 1.0, v112
	v_add_f32_e32 v108, v108, v140
	v_rcp_f32_e32 v106, v107
	v_mul_f32_e32 v108, 0xbfb8aa3b, v108
	v_mul_f32_e32 v117, 0x3f1b4598, v106
	v_exp_f32_e32 v108, v108
	s_nop 0
	v_add_f32_e32 v108, 1.0, v108
	v_add_f32_e32 v113, v113, v145
	v_rcp_f32_e32 v106, v112
	v_mul_f32_e32 v113, 0xbfb8aa3b, v113
	v_mul_f32_e32 v112, 0x3f1b4598, v106
	v_exp_f32_e32 v113, v113
	s_nop 0
	v_add_f32_e32 v113, 1.0, v113
	v_rcp_f32_e32 v106, v108
	v_add_f32_e32 v108, v109, v141
	v_mul_f32_e32 v108, 0xbfb8aa3b, v108
	v_exp_f32_e32 v108, v108
	v_mul_f32_e32 v119, 0x3f1b4598, v106
	v_add_f32_e32 v108, 1.0, v108
	v_rcp_f32_e32 v106, v113
	s_nop 0
	v_mul_f32_e32 v113, 0x3f1b4598, v106
	v_add_f32_e32 v102, v102, v142
	v_mul_f32_e32 v102, 0xbfb8aa3b, v102
	v_exp_f32_e32 v102, v102
	s_nop 0
	v_add_f32_e32 v102, 1.0, v102
	v_rcp_f32_e32 v106, v108
	v_cvt_pk_bf16_f32 v109, v112, v113
	v_mul_f32_e32 v118, 0x3f1b4598, v106
	v_or_b32_e32 v106, 32, v162
	v_ashrrev_i32_e32 v107, 31, v106
	v_add_f32_e32 v98, v98, v138
	v_lshlrev_b64 v[106:107], 11, v[106:107]
	v_mul_f32_e32 v98, 0xbfb8aa3b, v98
	v_mul_f32_e32 v110, 0x3f1b4598, v110
	v_lshl_add_u64 v[106:107], v[160:161], 0, v[106:107]
	v_cvt_pk_bf16_f32 v108, v110, v111
	v_exp_f32_e32 v98, v98
	v_cvt_pk_bf16_f32 v110, v116, v117
	v_cvt_pk_bf16_f32 v111, v119, v118
	global_store_dwordx4 v[106:107], v[108:111], off
	v_add_f32_e32 v98, 1.0, v98
	v_add_f32_e32 v103, v103, v143
	v_mul_f32_e32 v103, 0xbfb8aa3b, v103
	v_rcp_f32_e32 v102, v102
	v_exp_f32_e32 v103, v103
	s_nop 0
	v_add_f32_e32 v103, 1.0, v103
	v_add_f32_e32 v99, v99, v139
	v_rcp_f32_e32 v98, v98
	v_mul_f32_e32 v99, 0xbfb8aa3b, v99
	v_mul_f32_e32 v108, 0x3f1b4598, v98
	v_exp_f32_e32 v99, v99
	s_nop 0
	v_add_f32_e32 v99, 1.0, v99
	v_add_f32_e32 v104, v104, v144
	v_rcp_f32_e32 v98, v103
	v_mul_f32_e32 v104, 0xbfb8aa3b, v104
	v_mul_f32_e32 v103, 0x3f1b4598, v98
	v_exp_f32_e32 v104, v104
	s_nop 0
	v_add_f32_e32 v104, 1.0, v104
	v_add_f32_e32 v100, v100, v140
	v_rcp_f32_e32 v98, v99
	v_mul_f32_e32 v100, 0xbfb8aa3b, v100
	v_mul_f32_e32 v109, 0x3f1b4598, v98
	v_exp_f32_e32 v100, v100
	s_nop 0
	v_add_f32_e32 v100, 1.0, v100
	v_add_f32_e32 v105, v105, v145
	v_rcp_f32_e32 v98, v104
	v_mul_f32_e32 v105, 0xbfb8aa3b, v105
	v_mul_f32_e32 v104, 0x3f1b4598, v98
	v_exp_f32_e32 v105, v105
	s_nop 0
	v_add_f32_e32 v105, 1.0, v105
	v_rcp_f32_e32 v98, v100
	v_add_f32_e32 v100, v101, v141
	v_mul_f32_e32 v100, 0xbfb8aa3b, v100
	v_exp_f32_e32 v100, v100
	v_mul_f32_e32 v111, 0x3f1b4598, v98
	v_add_f32_e32 v100, 1.0, v100
	v_rcp_f32_e32 v98, v105
	s_nop 0
	v_mul_f32_e32 v105, 0x3f1b4598, v98
	v_add_f32_e32 v94, v94, v142
	v_mul_f32_e32 v94, 0xbfb8aa3b, v94
	v_exp_f32_e32 v94, v94
	s_nop 0
	v_add_f32_e32 v94, 1.0, v94
	v_rcp_f32_e32 v98, v100
	v_cvt_pk_bf16_f32 v101, v104, v105
	v_mul_f32_e32 v110, 0x3f1b4598, v98
	v_or_b32_e32 v98, 48, v162
	v_ashrrev_i32_e32 v99, 31, v98
	v_add_f32_e32 v90, v90, v138
	v_lshlrev_b64 v[98:99], 11, v[98:99]
	v_mul_f32_e32 v90, 0xbfb8aa3b, v90
	v_mul_f32_e32 v102, 0x3f1b4598, v102
	v_lshl_add_u64 v[98:99], v[160:161], 0, v[98:99]
	v_cvt_pk_bf16_f32 v100, v102, v103
	v_exp_f32_e32 v90, v90
	v_cvt_pk_bf16_f32 v102, v108, v109
	v_cvt_pk_bf16_f32 v103, v111, v110
	global_store_dwordx4 v[98:99], v[100:103], off
	v_add_f32_e32 v90, 1.0, v90
	v_add_f32_e32 v95, v95, v143
	v_mul_f32_e32 v95, 0xbfb8aa3b, v95
	v_rcp_f32_e32 v94, v94
	v_exp_f32_e32 v95, v95
	s_nop 0
	v_add_f32_e32 v95, 1.0, v95
	v_add_f32_e32 v91, v91, v139
	v_rcp_f32_e32 v90, v90
	v_mul_f32_e32 v91, 0xbfb8aa3b, v91
	v_mul_f32_e32 v100, 0x3f1b4598, v90
	v_exp_f32_e32 v91, v91
	s_nop 0
	v_add_f32_e32 v91, 1.0, v91
	v_add_f32_e32 v96, v96, v144
	v_rcp_f32_e32 v90, v95
	v_mul_f32_e32 v96, 0xbfb8aa3b, v96
	v_mul_f32_e32 v95, 0x3f1b4598, v90
	v_exp_f32_e32 v96, v96
	s_nop 0
	v_add_f32_e32 v96, 1.0, v96
	v_add_f32_e32 v92, v92, v140
	v_rcp_f32_e32 v90, v91
	v_mul_f32_e32 v92, 0xbfb8aa3b, v92
	v_mul_f32_e32 v101, 0x3f1b4598, v90
	v_exp_f32_e32 v92, v92
	s_nop 0
	v_add_f32_e32 v92, 1.0, v92
	v_add_f32_e32 v97, v97, v145
	v_rcp_f32_e32 v90, v96
	v_mul_f32_e32 v97, 0xbfb8aa3b, v97
	v_mul_f32_e32 v96, 0x3f1b4598, v90
	v_exp_f32_e32 v97, v97
	s_nop 0
	v_add_f32_e32 v97, 1.0, v97
	v_rcp_f32_e32 v90, v92
	v_add_f32_e32 v92, v93, v141
	v_mul_f32_e32 v92, 0xbfb8aa3b, v92
	v_exp_f32_e32 v92, v92
	v_mul_f32_e32 v103, 0x3f1b4598, v90
	v_add_f32_e32 v92, 1.0, v92
	v_rcp_f32_e32 v90, v97
	s_nop 0
	v_mul_f32_e32 v97, 0x3f1b4598, v90
	v_add_f32_e32 v86, v86, v142
	v_mul_f32_e32 v86, 0xbfb8aa3b, v86
	v_exp_f32_e32 v86, v86
	v_mul_f32_e32 v94, 0x3f1b4598, v94
	v_add_f32_e32 v86, 1.0, v86
	v_rcp_f32_e32 v90, v92
	v_cvt_pk_bf16_f32 v92, v94, v95
	v_cvt_pk_bf16_f32 v94, v100, v101
	v_add_f32_e32 v82, v82, v138
	v_cvt_pk_bf16_f32 v93, v96, v97
	v_add_co_u32_e32 v96, vcc, s90, v122
	v_mul_f32_e32 v82, 0xbfb8aa3b, v82
	s_nop 0
	v_addc_co_u32_e32 v97, vcc, 0, v123, vcc
	v_exp_f32_e32 v82, v82
	v_mul_f32_e32 v102, 0x3f1b4598, v90
	v_cvt_pk_bf16_f32 v95, v103, v102
	global_store_dwordx4 v[96:97], v[92:95], off
	v_add_f32_e32 v82, 1.0, v82
	v_add_f32_e32 v87, v87, v143
	v_mul_f32_e32 v87, 0xbfb8aa3b, v87
	v_rcp_f32_e32 v86, v86
	v_exp_f32_e32 v87, v87
	s_nop 0
	v_add_f32_e32 v87, 1.0, v87
	v_add_f32_e32 v83, v83, v139
	v_rcp_f32_e32 v82, v82
	v_mul_f32_e32 v83, 0xbfb8aa3b, v83
	v_mul_f32_e32 v92, 0x3f1b4598, v82
	v_exp_f32_e32 v83, v83
	s_nop 0
	v_add_f32_e32 v83, 1.0, v83
	v_add_f32_e32 v88, v88, v144
	v_rcp_f32_e32 v82, v87
	v_mul_f32_e32 v88, 0xbfb8aa3b, v88
	v_mul_f32_e32 v87, 0x3f1b4598, v82
	v_exp_f32_e32 v88, v88
	s_nop 0
	v_add_f32_e32 v88, 1.0, v88
	v_add_f32_e32 v84, v84, v140
	v_rcp_f32_e32 v82, v83
	v_mul_f32_e32 v84, 0xbfb8aa3b, v84
	v_mul_f32_e32 v93, 0x3f1b4598, v82
	v_exp_f32_e32 v84, v84
	s_nop 0
	v_add_f32_e32 v84, 1.0, v84
	v_add_f32_e32 v89, v89, v145
	v_rcp_f32_e32 v82, v88
	v_mul_f32_e32 v89, 0xbfb8aa3b, v89
	v_mul_f32_e32 v88, 0x3f1b4598, v82
	v_exp_f32_e32 v89, v89
	s_nop 0
	v_add_f32_e32 v89, 1.0, v89
	v_rcp_f32_e32 v82, v84
	v_add_f32_e32 v84, v85, v141
	v_mul_f32_e32 v84, 0xbfb8aa3b, v84
	v_exp_f32_e32 v84, v84
	v_mul_f32_e32 v95, 0x3f1b4598, v82
	v_add_f32_e32 v84, 1.0, v84
	v_rcp_f32_e32 v82, v89
	s_nop 0
	v_mul_f32_e32 v89, 0x3f1b4598, v82
	v_add_f32_e32 v78, v78, v142
	v_mul_f32_e32 v78, 0xbfb8aa3b, v78
	v_exp_f32_e32 v78, v78
	v_mul_f32_e32 v86, 0x3f1b4598, v86
	v_add_f32_e32 v78, 1.0, v78
	v_rcp_f32_e32 v82, v84
	v_cvt_pk_bf16_f32 v84, v86, v87
	v_cvt_pk_bf16_f32 v86, v92, v93
	v_add_f32_e32 v74, v74, v138
	v_cvt_pk_bf16_f32 v85, v88, v89
	v_add_co_u32_e32 v88, vcc, s91, v122
	v_mul_f32_e32 v74, 0xbfb8aa3b, v74
	s_nop 0
	v_addc_co_u32_e32 v89, vcc, 0, v123, vcc
	v_exp_f32_e32 v74, v74
	v_mul_f32_e32 v94, 0x3f1b4598, v82
	v_cvt_pk_bf16_f32 v87, v95, v94
	global_store_dwordx4 v[88:89], v[84:87], off
	v_add_f32_e32 v74, 1.0, v74
	v_add_f32_e32 v79, v79, v143
	v_mul_f32_e32 v79, 0xbfb8aa3b, v79
	v_rcp_f32_e32 v78, v78
	v_exp_f32_e32 v79, v79
	s_nop 0
	v_add_f32_e32 v79, 1.0, v79
	v_add_f32_e32 v75, v75, v139
	v_rcp_f32_e32 v74, v74
	v_mul_f32_e32 v75, 0xbfb8aa3b, v75
	v_mul_f32_e32 v84, 0x3f1b4598, v74
	v_exp_f32_e32 v75, v75
	s_nop 0
	v_add_f32_e32 v75, 1.0, v75
	v_add_f32_e32 v80, v80, v144
	v_rcp_f32_e32 v74, v79
	v_mul_f32_e32 v80, 0xbfb8aa3b, v80
	v_mul_f32_e32 v79, 0x3f1b4598, v74
	v_exp_f32_e32 v80, v80
	s_nop 0
	v_add_f32_e32 v80, 1.0, v80
	v_add_f32_e32 v76, v76, v140
	v_rcp_f32_e32 v74, v75
	v_mul_f32_e32 v76, 0xbfb8aa3b, v76
	v_mul_f32_e32 v85, 0x3f1b4598, v74
	v_exp_f32_e32 v76, v76
	s_nop 0
	v_add_f32_e32 v76, 1.0, v76
	v_add_f32_e32 v81, v81, v145
	v_rcp_f32_e32 v74, v80
	v_mul_f32_e32 v81, 0xbfb8aa3b, v81
	v_mul_f32_e32 v80, 0x3f1b4598, v74
	v_exp_f32_e32 v81, v81
	s_nop 0
	v_add_f32_e32 v81, 1.0, v81
	v_rcp_f32_e32 v74, v76
	v_add_f32_e32 v76, v77, v141
	v_mul_f32_e32 v76, 0xbfb8aa3b, v76
	v_exp_f32_e32 v76, v76
	v_mul_f32_e32 v87, 0x3f1b4598, v74
	v_add_f32_e32 v76, 1.0, v76
	v_rcp_f32_e32 v74, v81
	s_nop 0
	v_mul_f32_e32 v81, 0x3f1b4598, v74
	v_add_f32_e32 v70, v70, v142
	v_mul_f32_e32 v70, 0xbfb8aa3b, v70
	v_exp_f32_e32 v70, v70
	v_mul_f32_e32 v78, 0x3f1b4598, v78
	v_add_f32_e32 v70, 1.0, v70
	v_rcp_f32_e32 v74, v76
	v_cvt_pk_bf16_f32 v76, v78, v79
	v_cvt_pk_bf16_f32 v78, v84, v85
	v_add_f32_e32 v66, v66, v138
	v_cvt_pk_bf16_f32 v77, v80, v81
	v_add_co_u32_e32 v80, vcc, s92, v122
	v_mul_f32_e32 v66, 0xbfb8aa3b, v66
	s_nop 0
	v_addc_co_u32_e32 v81, vcc, 0, v123, vcc
	v_exp_f32_e32 v66, v66
	v_mul_f32_e32 v86, 0x3f1b4598, v74
	v_cvt_pk_bf16_f32 v79, v87, v86
	global_store_dwordx4 v[80:81], v[76:79], off
	v_add_f32_e32 v66, 1.0, v66
	v_add_f32_e32 v71, v71, v143
	v_mul_f32_e32 v71, 0xbfb8aa3b, v71
	v_rcp_f32_e32 v70, v70
	v_exp_f32_e32 v71, v71
	s_nop 0
	v_add_f32_e32 v71, 1.0, v71
	v_add_f32_e32 v67, v67, v139
	v_rcp_f32_e32 v66, v66
	v_mul_f32_e32 v67, 0xbfb8aa3b, v67
	v_mul_f32_e32 v76, 0x3f1b4598, v66
	v_exp_f32_e32 v67, v67
	s_nop 0
	v_add_f32_e32 v67, 1.0, v67
	v_add_f32_e32 v72, v72, v144
	v_rcp_f32_e32 v66, v71
	v_mul_f32_e32 v72, 0xbfb8aa3b, v72
	v_mul_f32_e32 v71, 0x3f1b4598, v66
	v_exp_f32_e32 v72, v72
	s_nop 0
	v_add_f32_e32 v72, 1.0, v72
	v_add_f32_e32 v68, v68, v140
	v_rcp_f32_e32 v66, v67
	v_mul_f32_e32 v68, 0xbfb8aa3b, v68
	v_mul_f32_e32 v77, 0x3f1b4598, v66
	v_exp_f32_e32 v68, v68
	s_nop 0
	v_add_f32_e32 v68, 1.0, v68
	v_add_f32_e32 v73, v73, v145
	v_rcp_f32_e32 v66, v72
	v_mul_f32_e32 v73, 0xbfb8aa3b, v73
	v_mul_f32_e32 v72, 0x3f1b4598, v66
	v_exp_f32_e32 v73, v73
	s_nop 0
	v_add_f32_e32 v73, 1.0, v73
	v_rcp_f32_e32 v66, v68
	v_add_f32_e32 v68, v69, v141
	v_mul_f32_e32 v68, 0xbfb8aa3b, v68
	v_exp_f32_e32 v68, v68
	v_mul_f32_e32 v79, 0x3f1b4598, v66
	v_add_f32_e32 v68, 1.0, v68
	v_rcp_f32_e32 v66, v73
	s_nop 0
	v_mul_f32_e32 v73, 0x3f1b4598, v66
	v_add_f32_e32 v62, v62, v134
	v_mul_f32_e32 v62, 0xbfb8aa3b, v62
	v_exp_f32_e32 v62, v62
	v_mul_f32_e32 v70, 0x3f1b4598, v70
	v_add_f32_e32 v62, 1.0, v62
	v_rcp_f32_e32 v66, v68
	v_cvt_pk_bf16_f32 v68, v70, v71
	v_cvt_pk_bf16_f32 v70, v76, v77
	v_add_f32_e32 v58, v58, v130
	v_cvt_pk_bf16_f32 v69, v72, v73
	v_add_co_u32_e32 v72, vcc, s93, v122
	v_mul_f32_e32 v58, 0xbfb8aa3b, v58
	s_nop 0
	v_addc_co_u32_e32 v73, vcc, 0, v123, vcc
	v_exp_f32_e32 v58, v58
	v_mul_f32_e32 v78, 0x3f1b4598, v66
	v_cvt_pk_bf16_f32 v71, v79, v78
	global_store_dwordx4 v[72:73], v[68:71], off
	v_add_f32_e32 v58, 1.0, v58
	v_add_f32_e32 v63, v63, v135
	v_mul_f32_e32 v63, 0xbfb8aa3b, v63
	v_rcp_f32_e32 v62, v62
	v_exp_f32_e32 v63, v63
	s_nop 0
	v_add_f32_e32 v63, 1.0, v63
	v_add_f32_e32 v59, v59, v131
	v_rcp_f32_e32 v58, v58
	v_mul_f32_e32 v59, 0xbfb8aa3b, v59
	v_mul_f32_e32 v68, 0x3f1b4598, v58
	v_exp_f32_e32 v59, v59
	s_nop 0
	v_add_f32_e32 v59, 1.0, v59
	v_add_f32_e32 v64, v64, v136
	v_mul_f32_e32 v64, 0xbfb8aa3b, v64
	v_rcp_f32_e32 v58, v63
	v_exp_f32_e32 v64, v64
	s_nop 0
	v_add_f32_e32 v64, 1.0, v64
	v_add_f32_e32 v60, v60, v132
	v_rcp_f32_e32 v59, v59
	v_mul_f32_e32 v60, 0xbfb8aa3b, v60
	v_mul_f32_e32 v63, 0x3f1b4598, v59
	v_exp_f32_e32 v60, v60
	s_nop 0
	v_add_f32_e32 v60, 1.0, v60
	v_add_f32_e32 v65, v65, v137
	v_mul_f32_e32 v65, 0xbfb8aa3b, v65
	v_rcp_f32_e32 v59, v64
	v_exp_f32_e32 v65, v65
	s_nop 0
	v_add_f32_e32 v65, 1.0, v65
	v_add_f32_e32 v61, v61, v133
	v_rcp_f32_e32 v60, v60
	v_mul_f32_e32 v61, 0xbfb8aa3b, v61
	v_mul_f32_e32 v64, 0x3f1b4598, v60
	v_exp_f32_e32 v61, v61
	s_nop 0
	v_add_f32_e32 v61, 1.0, v61
	v_add_f32_e32 v54, v54, v134
	v_rcp_f32_e32 v60, v65
	v_mul_f32_e32 v54, 0xbfb8aa3b, v54
	v_exp_f32_e32 v54, v54
	v_mul_f32_e32 v62, 0x3f1b4598, v62
	v_mul_f32_e32 v58, 0x3f1b4598, v58
	v_add_f32_e32 v54, 1.0, v54
	v_cvt_pk_bf16_f32 v58, v62, v58
	v_rcp_f32_e32 v61, v61
	v_add_f32_e32 v50, v50, v130
	v_mul_f32_e32 v50, 0xbfb8aa3b, v50
	v_mul_f32_e32 v59, 0x3f1b4598, v59
	v_mul_f32_e32 v60, 0x3f1b4598, v60
	v_mul_f32_e32 v61, 0x3f1b4598, v61
	v_exp_f32_e32 v50, v50
	v_cvt_pk_bf16_f32 v59, v59, v60
	v_cvt_pk_bf16_f32 v60, v68, v63
	v_cvt_pk_bf16_f32 v61, v64, v61
	global_store_dwordx4 v[122:123], v[58:61], off offset:256
	v_add_f32_e32 v50, 1.0, v50
	v_add_f32_e32 v55, v55, v135
	v_mul_f32_e32 v55, 0xbfb8aa3b, v55
	v_rcp_f32_e32 v54, v54
	v_exp_f32_e32 v55, v55
	s_nop 0
	v_add_f32_e32 v55, 1.0, v55
	v_add_f32_e32 v51, v51, v131
	v_rcp_f32_e32 v50, v50
	v_mul_f32_e32 v51, 0xbfb8aa3b, v51
	v_mul_f32_e32 v58, 0x3f1b4598, v50
	v_exp_f32_e32 v51, v51
	s_nop 0
	v_add_f32_e32 v51, 1.0, v51
	v_add_f32_e32 v56, v56, v136
	v_mul_f32_e32 v56, 0xbfb8aa3b, v56
	v_rcp_f32_e32 v50, v55
	v_exp_f32_e32 v56, v56
	s_nop 0
	v_add_f32_e32 v56, 1.0, v56
	v_add_f32_e32 v52, v52, v132
	v_rcp_f32_e32 v51, v51
	v_mul_f32_e32 v52, 0xbfb8aa3b, v52
	v_mul_f32_e32 v55, 0x3f1b4598, v51
	v_exp_f32_e32 v52, v52
	s_nop 0
	v_add_f32_e32 v52, 1.0, v52
	v_add_f32_e32 v57, v57, v137
	v_mul_f32_e32 v57, 0xbfb8aa3b, v57
	v_rcp_f32_e32 v51, v56
	v_exp_f32_e32 v57, v57
	s_nop 0
	v_add_f32_e32 v57, 1.0, v57
	v_add_f32_e32 v53, v53, v133
	v_rcp_f32_e32 v52, v52
	v_mul_f32_e32 v53, 0xbfb8aa3b, v53
	v_mul_f32_e32 v56, 0x3f1b4598, v52
	v_exp_f32_e32 v53, v53
	s_nop 0
	v_add_f32_e32 v53, 1.0, v53
	v_add_f32_e32 v46, v46, v134
	v_rcp_f32_e32 v52, v57
	v_mul_f32_e32 v46, 0xbfb8aa3b, v46
	v_exp_f32_e32 v46, v46
	v_mul_f32_e32 v54, 0x3f1b4598, v54
	v_mul_f32_e32 v50, 0x3f1b4598, v50
	v_add_f32_e32 v46, 1.0, v46
	v_cvt_pk_bf16_f32 v50, v54, v50
	v_rcp_f32_e32 v53, v53
	v_add_f32_e32 v42, v42, v130
	v_mul_f32_e32 v42, 0xbfb8aa3b, v42
	v_mul_f32_e32 v51, 0x3f1b4598, v51
	v_mul_f32_e32 v52, 0x3f1b4598, v52
	v_mul_f32_e32 v53, 0x3f1b4598, v53
	v_exp_f32_e32 v42, v42
	v_cvt_pk_bf16_f32 v51, v51, v52
	v_cvt_pk_bf16_f32 v52, v58, v55
	v_cvt_pk_bf16_f32 v53, v56, v53
	global_store_dwordx4 v[114:115], v[50:53], off offset:256
	v_add_f32_e32 v42, 1.0, v42
	v_add_f32_e32 v47, v47, v135
	v_mul_f32_e32 v47, 0xbfb8aa3b, v47
	v_rcp_f32_e32 v46, v46
	v_exp_f32_e32 v47, v47
	s_nop 0
	v_add_f32_e32 v47, 1.0, v47
	v_add_f32_e32 v43, v43, v131
	v_rcp_f32_e32 v42, v42
	v_mul_f32_e32 v43, 0xbfb8aa3b, v43
	v_mul_f32_e32 v50, 0x3f1b4598, v42
	v_exp_f32_e32 v43, v43
	s_nop 0
	v_add_f32_e32 v43, 1.0, v43
	v_add_f32_e32 v48, v48, v136
	v_mul_f32_e32 v48, 0xbfb8aa3b, v48
	v_rcp_f32_e32 v42, v47
	v_exp_f32_e32 v48, v48
	s_nop 0
	v_add_f32_e32 v48, 1.0, v48
	v_add_f32_e32 v44, v44, v132
	v_rcp_f32_e32 v43, v43
	v_mul_f32_e32 v44, 0xbfb8aa3b, v44
	v_mul_f32_e32 v47, 0x3f1b4598, v43
	v_exp_f32_e32 v44, v44
	s_nop 0
	v_add_f32_e32 v44, 1.0, v44
	v_add_f32_e32 v49, v49, v137
	v_mul_f32_e32 v49, 0xbfb8aa3b, v49
	v_rcp_f32_e32 v43, v48
	v_exp_f32_e32 v49, v49
	s_nop 0
	v_add_f32_e32 v49, 1.0, v49
	v_add_f32_e32 v45, v45, v133
	v_rcp_f32_e32 v44, v44
	v_mul_f32_e32 v45, 0xbfb8aa3b, v45
	v_mul_f32_e32 v48, 0x3f1b4598, v44
	v_exp_f32_e32 v45, v45
	s_nop 0
	v_add_f32_e32 v45, 1.0, v45
	v_add_f32_e32 v38, v38, v134
	v_rcp_f32_e32 v44, v49
	v_mul_f32_e32 v38, 0xbfb8aa3b, v38
	v_exp_f32_e32 v38, v38
	v_mul_f32_e32 v46, 0x3f1b4598, v46
	v_mul_f32_e32 v42, 0x3f1b4598, v42
	v_add_f32_e32 v38, 1.0, v38
	v_cvt_pk_bf16_f32 v42, v46, v42
	v_rcp_f32_e32 v45, v45
	v_add_f32_e32 v34, v34, v130
	v_mul_f32_e32 v34, 0xbfb8aa3b, v34
	v_mul_f32_e32 v43, 0x3f1b4598, v43
	v_mul_f32_e32 v44, 0x3f1b4598, v44
	v_mul_f32_e32 v45, 0x3f1b4598, v45
	v_exp_f32_e32 v34, v34
	v_cvt_pk_bf16_f32 v43, v43, v44
	v_cvt_pk_bf16_f32 v44, v50, v47
	v_cvt_pk_bf16_f32 v45, v48, v45
	global_store_dwordx4 v[106:107], v[42:45], off offset:256
	v_add_f32_e32 v34, 1.0, v34
	v_add_f32_e32 v39, v39, v135
	v_mul_f32_e32 v39, 0xbfb8aa3b, v39
	v_rcp_f32_e32 v38, v38
	v_exp_f32_e32 v39, v39
	s_nop 0
	v_add_f32_e32 v39, 1.0, v39
	v_add_f32_e32 v35, v35, v131
	v_rcp_f32_e32 v34, v34
	v_mul_f32_e32 v35, 0xbfb8aa3b, v35
	v_mul_f32_e32 v42, 0x3f1b4598, v34
	v_exp_f32_e32 v35, v35
	s_nop 0
	v_add_f32_e32 v35, 1.0, v35
	v_add_f32_e32 v40, v40, v136
	v_mul_f32_e32 v40, 0xbfb8aa3b, v40
	v_rcp_f32_e32 v34, v39
	v_exp_f32_e32 v40, v40
	s_nop 0
	v_add_f32_e32 v40, 1.0, v40
	v_add_f32_e32 v36, v36, v132
	v_rcp_f32_e32 v35, v35
	v_mul_f32_e32 v36, 0xbfb8aa3b, v36
	v_mul_f32_e32 v39, 0x3f1b4598, v35
	v_exp_f32_e32 v36, v36
	s_nop 0
	v_add_f32_e32 v36, 1.0, v36
	v_add_f32_e32 v41, v41, v137
	v_mul_f32_e32 v41, 0xbfb8aa3b, v41
	v_rcp_f32_e32 v35, v40
	v_exp_f32_e32 v41, v41
	s_nop 0
	v_add_f32_e32 v41, 1.0, v41
	v_add_f32_e32 v37, v37, v133
	v_rcp_f32_e32 v36, v36
	v_mul_f32_e32 v37, 0xbfb8aa3b, v37
	v_mul_f32_e32 v40, 0x3f1b4598, v36
	v_exp_f32_e32 v37, v37
	s_nop 0
	v_add_f32_e32 v37, 1.0, v37
	v_add_f32_e32 v30, v30, v134
	v_rcp_f32_e32 v36, v41
	v_mul_f32_e32 v30, 0xbfb8aa3b, v30
	v_exp_f32_e32 v30, v30
	v_mul_f32_e32 v38, 0x3f1b4598, v38
	v_mul_f32_e32 v34, 0x3f1b4598, v34
	v_add_f32_e32 v30, 1.0, v30
	v_cvt_pk_bf16_f32 v34, v38, v34
	v_rcp_f32_e32 v37, v37
	v_add_f32_e32 v26, v26, v130
	v_mul_f32_e32 v26, 0xbfb8aa3b, v26
	v_mul_f32_e32 v35, 0x3f1b4598, v35
	v_mul_f32_e32 v36, 0x3f1b4598, v36
	v_mul_f32_e32 v37, 0x3f1b4598, v37
	v_exp_f32_e32 v26, v26
	v_cvt_pk_bf16_f32 v35, v35, v36
	v_cvt_pk_bf16_f32 v36, v42, v39
	v_cvt_pk_bf16_f32 v37, v40, v37
	global_store_dwordx4 v[98:99], v[34:37], off offset:256
	v_add_f32_e32 v26, 1.0, v26
	v_add_f32_e32 v31, v31, v135
	v_mul_f32_e32 v31, 0xbfb8aa3b, v31
	v_rcp_f32_e32 v30, v30
	v_exp_f32_e32 v31, v31
	s_nop 0
	v_add_f32_e32 v31, 1.0, v31
	v_add_f32_e32 v27, v27, v131
	v_rcp_f32_e32 v26, v26
	v_mul_f32_e32 v27, 0xbfb8aa3b, v27
	v_mul_f32_e32 v34, 0x3f1b4598, v26
	v_exp_f32_e32 v27, v27
	s_nop 0
	v_add_f32_e32 v27, 1.0, v27
	v_add_f32_e32 v32, v32, v136
	v_mul_f32_e32 v32, 0xbfb8aa3b, v32
	v_rcp_f32_e32 v26, v31
	v_exp_f32_e32 v32, v32
	s_nop 0
	v_add_f32_e32 v32, 1.0, v32
	v_add_f32_e32 v28, v28, v132
	v_rcp_f32_e32 v27, v27
	v_mul_f32_e32 v28, 0xbfb8aa3b, v28
	v_mul_f32_e32 v31, 0x3f1b4598, v27
	v_exp_f32_e32 v28, v28
	s_nop 0
	v_add_f32_e32 v28, 1.0, v28
	v_add_f32_e32 v33, v33, v137
	v_mul_f32_e32 v33, 0xbfb8aa3b, v33
	v_rcp_f32_e32 v27, v32
	v_exp_f32_e32 v33, v33
	s_nop 0
	v_add_f32_e32 v33, 1.0, v33
	v_add_f32_e32 v29, v29, v133
	v_rcp_f32_e32 v28, v28
	v_mul_f32_e32 v29, 0xbfb8aa3b, v29
	v_mul_f32_e32 v32, 0x3f1b4598, v28
	v_exp_f32_e32 v29, v29
	s_nop 0
	v_add_f32_e32 v29, 1.0, v29
	v_add_f32_e32 v22, v22, v134
	v_rcp_f32_e32 v28, v33
	v_mul_f32_e32 v22, 0xbfb8aa3b, v22
	v_exp_f32_e32 v22, v22
	v_mul_f32_e32 v30, 0x3f1b4598, v30
	v_mul_f32_e32 v26, 0x3f1b4598, v26
	v_add_f32_e32 v22, 1.0, v22
	v_cvt_pk_bf16_f32 v26, v30, v26
	v_rcp_f32_e32 v29, v29
	v_add_f32_e32 v18, v18, v130
	v_mul_f32_e32 v18, 0xbfb8aa3b, v18
	v_lshl_add_u64 v[90:91], v[122:123], 0, s[34:35]
	v_mul_f32_e32 v27, 0x3f1b4598, v27
	v_mul_f32_e32 v28, 0x3f1b4598, v28
	v_mul_f32_e32 v29, 0x3f1b4598, v29
	v_exp_f32_e32 v18, v18
	v_cvt_pk_bf16_f32 v27, v27, v28
	v_cvt_pk_bf16_f32 v28, v34, v31
	v_cvt_pk_bf16_f32 v29, v32, v29
	global_store_dwordx4 v[90:91], v[26:29], off offset:256
	v_add_f32_e32 v18, 1.0, v18
	v_add_f32_e32 v23, v23, v135
	v_mul_f32_e32 v23, 0xbfb8aa3b, v23
	v_rcp_f32_e32 v22, v22
	v_exp_f32_e32 v23, v23
	s_nop 0
	v_add_f32_e32 v23, 1.0, v23
	v_add_f32_e32 v19, v19, v131
	v_rcp_f32_e32 v18, v18
	v_mul_f32_e32 v19, 0xbfb8aa3b, v19
	v_mul_f32_e32 v26, 0x3f1b4598, v18
	v_exp_f32_e32 v19, v19
	s_nop 0
	v_add_f32_e32 v19, 1.0, v19
	v_add_f32_e32 v24, v24, v136
	v_mul_f32_e32 v24, 0xbfb8aa3b, v24
	v_rcp_f32_e32 v18, v23
	v_exp_f32_e32 v24, v24
	s_nop 0
	v_add_f32_e32 v24, 1.0, v24
	v_add_f32_e32 v20, v20, v132
	v_rcp_f32_e32 v19, v19
	v_mul_f32_e32 v20, 0xbfb8aa3b, v20
	v_mul_f32_e32 v23, 0x3f1b4598, v19
	v_exp_f32_e32 v20, v20
	s_nop 0
	v_add_f32_e32 v20, 1.0, v20
	v_add_f32_e32 v25, v25, v137
	v_mul_f32_e32 v25, 0xbfb8aa3b, v25
	v_rcp_f32_e32 v19, v24
	v_exp_f32_e32 v25, v25
	s_nop 0
	v_add_f32_e32 v25, 1.0, v25
	v_add_f32_e32 v21, v21, v133
	v_rcp_f32_e32 v20, v20
	v_mul_f32_e32 v21, 0xbfb8aa3b, v21
	v_mul_f32_e32 v24, 0x3f1b4598, v20
	v_exp_f32_e32 v21, v21
	s_nop 0
	v_add_f32_e32 v21, 1.0, v21
	v_add_f32_e32 v14, v14, v134
	v_rcp_f32_e32 v20, v25
	v_mul_f32_e32 v14, 0xbfb8aa3b, v14
	v_exp_f32_e32 v14, v14
	v_mul_f32_e32 v22, 0x3f1b4598, v22
	v_mul_f32_e32 v18, 0x3f1b4598, v18
	v_add_f32_e32 v14, 1.0, v14
	v_cvt_pk_bf16_f32 v18, v22, v18
	v_rcp_f32_e32 v21, v21
	v_add_f32_e32 v10, v10, v130
	v_mul_f32_e32 v10, 0xbfb8aa3b, v10
	v_lshl_add_u64 v[82:83], v[122:123], 0, s[36:37]
	v_mul_f32_e32 v19, 0x3f1b4598, v19
	v_mul_f32_e32 v20, 0x3f1b4598, v20
	v_mul_f32_e32 v21, 0x3f1b4598, v21
	v_exp_f32_e32 v10, v10
	v_cvt_pk_bf16_f32 v19, v19, v20
	v_cvt_pk_bf16_f32 v20, v26, v23
	v_cvt_pk_bf16_f32 v21, v24, v21
	global_store_dwordx4 v[82:83], v[18:21], off offset:256
	v_add_f32_e32 v10, 1.0, v10
	v_add_f32_e32 v15, v15, v135
	v_mul_f32_e32 v15, 0xbfb8aa3b, v15
	v_rcp_f32_e32 v14, v14
	v_exp_f32_e32 v15, v15
	s_nop 0
	v_add_f32_e32 v15, 1.0, v15
	v_add_f32_e32 v11, v11, v131
	v_rcp_f32_e32 v10, v10
	v_mul_f32_e32 v11, 0xbfb8aa3b, v11
	v_mul_f32_e32 v18, 0x3f1b4598, v10
	v_exp_f32_e32 v11, v11
	s_nop 0
	v_add_f32_e32 v11, 1.0, v11
	v_add_f32_e32 v16, v16, v136
	v_mul_f32_e32 v16, 0xbfb8aa3b, v16
	v_rcp_f32_e32 v10, v15
	v_exp_f32_e32 v16, v16
	s_nop 0
	v_add_f32_e32 v16, 1.0, v16
	v_add_f32_e32 v12, v12, v132
	v_rcp_f32_e32 v11, v11
	v_mul_f32_e32 v12, 0xbfb8aa3b, v12
	v_mul_f32_e32 v15, 0x3f1b4598, v11
	v_exp_f32_e32 v12, v12
	s_nop 0
	v_add_f32_e32 v12, 1.0, v12
	v_add_f32_e32 v17, v17, v137
	v_mul_f32_e32 v17, 0xbfb8aa3b, v17
	v_rcp_f32_e32 v11, v16
	v_exp_f32_e32 v17, v17
	s_nop 0
	v_add_f32_e32 v17, 1.0, v17
	v_add_f32_e32 v13, v13, v133
	v_rcp_f32_e32 v12, v12
	v_mul_f32_e32 v13, 0xbfb8aa3b, v13
	v_mul_f32_e32 v16, 0x3f1b4598, v12
	v_exp_f32_e32 v13, v13
	s_nop 0
	v_add_f32_e32 v13, 1.0, v13
	v_add_f32_e32 v6, v6, v134
	v_rcp_f32_e32 v12, v17
	v_mul_f32_e32 v6, 0xbfb8aa3b, v6
	v_exp_f32_e32 v6, v6
	v_mul_f32_e32 v14, 0x3f1b4598, v14
	v_mul_f32_e32 v10, 0x3f1b4598, v10
	v_add_f32_e32 v6, 1.0, v6
	v_cvt_pk_bf16_f32 v10, v14, v10
	v_rcp_f32_e32 v13, v13
	v_add_f32_e32 v2, v2, v130
	v_mul_f32_e32 v2, 0xbfb8aa3b, v2
	v_lshl_add_u64 v[74:75], v[122:123], 0, s[38:39]
	v_mul_f32_e32 v11, 0x3f1b4598, v11
	v_mul_f32_e32 v12, 0x3f1b4598, v12
	v_mul_f32_e32 v13, 0x3f1b4598, v13
	v_exp_f32_e32 v2, v2
	v_cvt_pk_bf16_f32 v11, v11, v12
	v_cvt_pk_bf16_f32 v12, v18, v15
	v_cvt_pk_bf16_f32 v13, v16, v13
	global_store_dwordx4 v[74:75], v[10:13], off offset:256
	v_add_f32_e32 v2, 1.0, v2
	v_add_f32_e32 v7, v7, v135
	v_mul_f32_e32 v7, 0xbfb8aa3b, v7
	v_rcp_f32_e32 v6, v6
	v_exp_f32_e32 v7, v7
	s_nop 0
	v_add_f32_e32 v7, 1.0, v7
	v_add_f32_e32 v3, v3, v131
	v_rcp_f32_e32 v2, v2
	v_mul_f32_e32 v3, 0xbfb8aa3b, v3
	v_mul_f32_e32 v10, 0x3f1b4598, v2
	v_exp_f32_e32 v3, v3
	s_nop 0
	v_add_f32_e32 v3, 1.0, v3
	v_add_f32_e32 v8, v8, v136
	v_mul_f32_e32 v8, 0xbfb8aa3b, v8
	v_rcp_f32_e32 v2, v7
	v_exp_f32_e32 v8, v8
	s_nop 0
	v_add_f32_e32 v8, 1.0, v8
	v_add_f32_e32 v4, v4, v132
	v_rcp_f32_e32 v3, v3
	v_mul_f32_e32 v4, 0xbfb8aa3b, v4
	v_mul_f32_e32 v7, 0x3f1b4598, v3
	v_exp_f32_e32 v4, v4
	s_nop 0
	v_add_f32_e32 v4, 1.0, v4
	v_add_f32_e32 v9, v9, v137
	v_mul_f32_e32 v9, 0xbfb8aa3b, v9
	v_rcp_f32_e32 v3, v8
	v_exp_f32_e32 v9, v9
	s_nop 0
	v_add_f32_e32 v9, 1.0, v9
	v_add_f32_e32 v5, v5, v133
	v_rcp_f32_e32 v4, v4
	v_mul_f32_e32 v5, 0xbfb8aa3b, v5
	v_mul_f32_e32 v8, 0x3f1b4598, v4
	v_exp_f32_e32 v5, v5
	s_nop 0
	v_add_f32_e32 v5, 1.0, v5
	v_rcp_f32_e32 v4, v9
	v_lshl_add_u64 v[66:67], v[122:123], 0, s[40:41]
	v_rcp_f32_e32 v5, v5
	v_mul_f32_e32 v2, 0x3f1b4598, v2
	v_mul_f32_e32 v3, 0x3f1b4598, v3
	v_mul_f32_e32 v4, 0x3f1b4598, v4
	v_mul_f32_e32 v5, 0x3f1b4598, v5
	v_mul_f32_e32 v6, 0x3f1b4598, v6
	v_cvt_pk_bf16_f32 v2, v6, v2
	v_cvt_pk_bf16_f32 v3, v3, v4
	v_cvt_pk_bf16_f32 v4, v10, v7
	v_cvt_pk_bf16_f32 v5, v8, v5
	global_store_dwordx4 v[66:67], v[2:5], off offset:256
	s_andn2_b64 vcc, exec, s[4:5]
	s_mov_b64 s[4:5], -1
	s_cbranch_vccnz .LBB0_996
